# LayerNorm epilogues: residual-row (xin) loads kept three batches in flight with counted waits instead of eight serial load->wait rounds
# baseline (speedup 1.0000x reference)
;     __device__ __forceinline__ void fused(f32x4 (&acc)[2][2][4][2], const Unit& u, int wr, int wc, int fr, int fq, PG8_LAS unsigned char* lds, int wid, int lane) const {
;     ...
;         const int col0 = u.pn * BM + wc * 32 + 4 * fq; const int b = (u.pm * BM) >> 13; const size_t mo = (size_t)b * 9216;
; #pragma unroll
;         for (int bj = 0; bj < 2; ++bj)
; #pragma unroll
;             for (int n = 0; n < 2; ++n) { const f32x4 gv = (*(const f32x4*)(gate + mo + col0 + bj * HALF + n * 16) + 1.0f) * coef;
; #pragma unroll
;                 for (int ai = 0; ai < 2; ++ai)
; #pragma unroll
;                     for (int m = 0; m < 4; ++m) acc[ai][bj][m][n] = acc[ai][bj][m][n] * gv; }
; #pragma unroll
;         for (int ai = 0; ai < 2; ++ai)
; #pragma unroll
;             for (int m = 0; m < 4; ++m) { const size_t off = (size_t)(u.pm * BM + ai * HALF + wr * 64 + m * 16 + fr) * 1024 + col0;
; #pragma unroll
;                 for (int bj = 0; bj < 2; ++bj)
; #pragma unroll
;                     for (int n = 0; n < 2; ++n) { const f32x4 xv = *(const f32x4*)(xin + off + bj * HALF + n * 16); acc[ai][bj][m][n] = xv * ALPHA_ + acc[ai][bj][m][n]; }
.LBB0_392:
	s_lshl_b32 s6, s21, 5
	s_lshl_b32 s7, s14, 8
	s_or_b32 s6, s7, s6
	v_lshrrev_b32_e32 v4, 2, v149
	v_and_or_b32 v154, v4, 12, s6
	s_ashr_i32 s6, s50, 5
	s_mul_hi_i32 s7, s6, 0x2400
	s_mulk_i32 s6, 0x2400
	s_lshl_b64 s[16:17], s[6:7], 2
	v_ashrrev_i32_e32 v155, 31, v154
	s_add_u32 s6, s12, s16
	s_addc_u32 s7, s13, s17
	v_lshlrev_b64 v[136:137], 2, v[154:155]
	v_lshl_add_u64 v[156:157], s[6:7], 0, v[136:137]
	s_mov_b64 s[6:7], 0x2000
	s_lshl_b32 s20, s50, 8
	v_lshl_add_u64 v[164:165], v[156:157], 0, s[6:7]
	s_add_i32 s6, s20, s60
	v_or_b32_e32 v172, s6, v151
	s_movk_i32 s8, 0x2000
	v_ashrrev_i32_e32 v173, 31, v172
	v_add_co_u32_e32 v4, vcc, s8, v156
	v_lshlrev_b64 v[168:169], 12, v[172:173]
	s_nop 0
	v_addc_co_u32_e32 v5, vcc, 0, v157, vcc
	s_waitcnt vmcnt(0) lgkmcnt(0)
	v_lshl_add_u64 v[168:169], v[138:139], 0, v[168:169]
	s_barrier
	global_load_dwordx4 v[4:7], v[4:5], off
	s_nop 0
	global_load_dwordx4 v[156:159], v[164:165], off offset:64
	global_load_dwordx4 v[160:163], v[164:165], off offset:512
	s_nop 0
	global_load_dwordx4 v[164:167], v[164:165], off offset:576
	v_lshl_add_u64 v[168:169], v[168:169], 0, v[136:137]
	global_load_dwordx4 v[174:177], v[168:169], off
	global_load_dwordx4 v[182:185], v[168:169], off offset:64
	global_load_dwordx4 v[186:189], v[168:169], off offset:512
	global_load_dwordx4 v[190:193], v[168:169], off offset:576
	v_mov_b32_e32 v246, 0x10000
	v_mov_b32_e32 v247, 0
	v_mov_b32_e32 v248, 0x50000
	v_mov_b32_e32 v249, 0
	v_lshl_add_u64 v[244:245], v[168:169], 0, v[246:247]
	global_load_dwordx4 v[204:207], v[244:245], off
	global_load_dwordx4 v[208:211], v[244:245], off offset:64
	global_load_dwordx4 v[220:223], v[244:245], off offset:512
	global_load_dwordx4 v[224:227], v[244:245], off offset:576
	v_lshl_add_u64 v[244:245], v[244:245], 0, v[246:247]
	global_load_dwordx4 v[228:231], v[244:245], off
	global_load_dwordx4 v[232:235], v[244:245], off offset:64
	global_load_dwordx4 v[236:239], v[244:245], off offset:512
	global_load_dwordx4 v[240:243], v[244:245], off offset:576
	v_or_b32_e32 v168, 16, v172
	v_ashrrev_i32_e32 v169, 31, v168
	v_lshlrev_b64 v[168:169], 12, v[168:169]
	v_lshl_add_u64 v[168:169], v[138:139], 0, v[168:169]
	s_mov_b32 s6, 0x3f9837f0
	v_lshl_add_u64 v[194:195], v[168:169], 0, v[136:137]
	s_waitcnt vmcnt(8) lgkmcnt(0)
	v_pk_add_f32 v[168:169], v[158:159], 1.0 op_sel_hi:[1,0]
	v_pk_add_f32 v[6:7], v[6:7], 1.0 op_sel_hi:[1,0]
	v_pk_add_f32 v[4:5], v[4:5], 1.0 op_sel_hi:[1,0]
	v_pk_add_f32 v[170:171], v[156:157], 1.0 op_sel_hi:[1,0]
	v_pk_add_f32 v[196:197], v[162:163], 1.0 op_sel_hi:[1,0]
	v_pk_add_f32 v[198:199], v[160:161], 1.0 op_sel_hi:[1,0]
	v_pk_add_f32 v[200:201], v[166:167], 1.0 op_sel_hi:[1,0]
	v_pk_add_f32 v[202:203], v[164:165], 1.0 op_sel_hi:[1,0]
	v_pk_mul_f32 v[156:157], v[6:7], 0.5 op_sel_hi:[1,0]
	v_pk_mul_f32 v[158:159], v[4:5], 0.5 op_sel_hi:[1,0]
	v_pk_mul_f32 v[160:161], v[168:169], 0.5 op_sel_hi:[1,0]
	v_pk_mul_f32 v[162:163], v[170:171], 0.5 op_sel_hi:[1,0]
	v_pk_mul_f32 v[164:165], v[196:197], 0.5 op_sel_hi:[1,0]
	v_pk_mul_f32 v[166:167], v[198:199], 0.5 op_sel_hi:[1,0]
	v_pk_mul_f32 v[168:169], v[200:201], 0.5 op_sel_hi:[1,0]
	v_pk_mul_f32 v[170:171], v[202:203], 0.5 op_sel_hi:[1,0]
	v_pk_mul_f32 v[4:5], v[176:177], s[6:7] op_sel_hi:[1,0]
	v_pk_mul_f32 v[6:7], v[174:175], s[6:7] op_sel_hi:[1,0]
	v_pk_mul_f32 v[174:175], v[184:185], s[6:7] op_sel_hi:[1,0]
	v_pk_mul_f32 v[176:177], v[182:183], s[6:7] op_sel_hi:[1,0]
	v_pk_mul_f32 v[182:183], v[188:189], s[6:7] op_sel_hi:[1,0]
	v_pk_mul_f32 v[184:185], v[186:187], s[6:7] op_sel_hi:[1,0]
	v_pk_mul_f32 v[186:187], v[192:193], s[6:7] op_sel_hi:[1,0]
	v_pk_mul_f32 v[188:189], v[190:191], s[6:7] op_sel_hi:[1,0]
	v_pk_fma_f32 v[94:95], v[94:95], v[156:157], v[4:5]
	v_pk_fma_f32 v[92:93], v[92:93], v[158:159], v[6:7]
	v_pk_fma_f32 v[62:63], v[62:63], v[160:161], v[174:175]
	v_pk_fma_f32 v[60:61], v[60:61], v[162:163], v[176:177]
	v_pk_fma_f32 v[30:31], v[30:31], v[164:165], v[182:183]
	v_pk_fma_f32 v[28:29], v[28:29], v[166:167], v[184:185]
	v_pk_fma_f32 v[6:7], v[134:135], v[168:169], v[186:187]
	v_pk_fma_f32 v[4:5], v[132:133], v[170:171], v[188:189]
	v_or_b32_e32 v190, 32, v172
	s_waitcnt vmcnt(4)
	v_mov_b64_e32 v[132:133], v[204:205]
	v_mov_b64_e32 v[134:135], v[206:207]
	v_mov_b64_e32 v[174:175], v[208:209]
	v_mov_b64_e32 v[176:177], v[210:211]
	v_mov_b64_e32 v[182:183], v[220:221]
	v_mov_b64_e32 v[184:185], v[222:223]
	v_mov_b64_e32 v[186:187], v[224:225]
	v_mov_b64_e32 v[188:189], v[226:227]
	v_lshl_add_u64 v[244:245], v[244:245], 0, v[246:247]
	global_load_dwordx4 v[204:207], v[244:245], off
	global_load_dwordx4 v[208:211], v[244:245], off offset:64
	global_load_dwordx4 v[220:223], v[244:245], off offset:512
	global_load_dwordx4 v[224:227], v[244:245], off offset:576
	v_ashrrev_i32_e32 v191, 31, v190
	v_lshlrev_b64 v[190:191], 12, v[190:191]
	v_lshl_add_u64 v[190:191], v[138:139], 0, v[190:191]
	v_lshl_add_u64 v[190:191], v[190:191], 0, v[136:137]
	v_mov_b32_e32 v194, v92
	v_mov_b32_e32 v195, v95
	v_mov_b32_e32 v196, v61
	v_mov_b32_e32 v197, v62
	v_add_f32_e32 v199, v30, v31
	v_mov_b32_e32 v198, v5
	v_mov_b32_e32 v200, v7
	s_waitcnt lgkmcnt(0)
;     __device__ __forceinline__ void fused(f32x4 (&acc)[2][2][4][2], const Unit& u, int wr, int wc, int fr, int fq, PG8_LAS unsigned char* lds, int wid, int lane) const {
;     ...
;         for (int ai = 0; ai < 2; ++ai)
; #pragma unroll
;             for (int m = 0; m < 4; ++m) { const size_t off = (size_t)(u.pm * BM + ai * HALF + wr * 64 + m * 16 + fr) * 1024 + col0;
; #pragma unroll
;                 for (int bj = 0; bj < 2; ++bj)
; #pragma unroll
;                     for (int n = 0; n < 2; ++n) { const f32x4 xv = *(const f32x4*)(xin + off + bj * HALF + n * 16); acc[ai][bj][m][n] = xv * ALPHA_ + acc[ai][bj][m][n]; }
;                 asm volatile("" : "+v"(acc[ai][0][m][0]), "+v"(acc[ai][0][m][1]), "+v"(acc[ai][1][m][0]), "+v"(acc[ai][1][m][1]));
;                 if (m & 1) asm volatile("" ::: "memory"); }
	v_pk_mul_f32 v[134:135], v[134:135], s[6:7] op_sel_hi:[1,0]
	v_pk_mul_f32 v[132:133], v[132:133], s[6:7] op_sel_hi:[1,0]
	v_pk_mul_f32 v[176:177], v[176:177], s[6:7] op_sel_hi:[1,0]
	v_pk_mul_f32 v[174:175], v[174:175], s[6:7] op_sel_hi:[1,0]
	v_pk_mul_f32 v[184:185], v[184:185], s[6:7] op_sel_hi:[1,0]
	v_pk_mul_f32 v[182:183], v[182:183], s[6:7] op_sel_hi:[1,0]
	v_pk_mul_f32 v[188:189], v[188:189], s[6:7] op_sel_hi:[1,0]
	v_pk_mul_f32 v[186:187], v[186:187], s[6:7] op_sel_hi:[1,0]
	v_pk_fma_f32 v[102:103], v[102:103], v[156:157], v[134:135]
	v_pk_fma_f32 v[100:101], v[100:101], v[158:159], v[132:133]
	v_pk_fma_f32 v[70:71], v[70:71], v[160:161], v[176:177]
	v_pk_fma_f32 v[68:69], v[68:69], v[162:163], v[174:175]
	v_pk_fma_f32 v[38:39], v[38:39], v[164:165], v[184:185]
	v_pk_fma_f32 v[36:37], v[36:37], v[166:167], v[182:183]
	v_pk_fma_f32 v[10:11], v[10:11], v[168:169], v[188:189]
	v_pk_fma_f32 v[8:9], v[8:9], v[170:171], v[186:187]
	s_nop 0
	s_waitcnt vmcnt(4)
	v_mov_b64_e32 v[132:133], v[228:229]
	v_mov_b64_e32 v[134:135], v[230:231]
	v_mov_b64_e32 v[174:175], v[232:233]
	v_mov_b64_e32 v[176:177], v[234:235]
	v_mov_b64_e32 v[182:183], v[236:237]
	v_mov_b64_e32 v[184:185], v[238:239]
	v_mov_b64_e32 v[186:187], v[240:241]
	v_mov_b64_e32 v[188:189], v[242:243]
	v_lshl_add_u64 v[244:245], v[244:245], 0, v[248:249]
	global_load_dwordx4 v[228:231], v[244:245], off
	global_load_dwordx4 v[232:235], v[244:245], off offset:64
	global_load_dwordx4 v[236:239], v[244:245], off offset:512
	global_load_dwordx4 v[240:243], v[244:245], off offset:576
	v_or_b32_e32 v190, 48, v172
	v_ashrrev_i32_e32 v191, 31, v190
	v_lshlrev_b64 v[190:191], 12, v[190:191]
	v_lshl_add_u64 v[190:191], v[138:139], 0, v[190:191]
	v_lshl_add_u64 v[190:191], v[190:191], 0, v[136:137]
	s_waitcnt lgkmcnt(0)
	v_pk_mul_f32 v[134:135], v[134:135], s[6:7] op_sel_hi:[1,0]
	v_pk_mul_f32 v[132:133], v[132:133], s[6:7] op_sel_hi:[1,0]
	v_pk_mul_f32 v[176:177], v[176:177], s[6:7] op_sel_hi:[1,0]
	v_pk_mul_f32 v[174:175], v[174:175], s[6:7] op_sel_hi:[1,0]
	v_pk_mul_f32 v[184:185], v[184:185], s[6:7] op_sel_hi:[1,0]
	v_pk_mul_f32 v[182:183], v[182:183], s[6:7] op_sel_hi:[1,0]
	v_pk_mul_f32 v[188:189], v[188:189], s[6:7] op_sel_hi:[1,0]
	v_pk_mul_f32 v[186:187], v[186:187], s[6:7] op_sel_hi:[1,0]
	v_pk_fma_f32 v[110:111], v[110:111], v[156:157], v[134:135]
	v_pk_fma_f32 v[108:109], v[108:109], v[158:159], v[132:133]
	v_pk_fma_f32 v[74:75], v[74:75], v[160:161], v[176:177]
	v_pk_fma_f32 v[72:73], v[72:73], v[162:163], v[174:175]
	v_pk_fma_f32 v[42:43], v[42:43], v[164:165], v[184:185]
	v_pk_fma_f32 v[40:41], v[40:41], v[166:167], v[182:183]
	v_pk_fma_f32 v[14:15], v[14:15], v[168:169], v[188:189]
	v_pk_fma_f32 v[12:13], v[12:13], v[170:171], v[186:187]
	s_nop 0
	s_waitcnt vmcnt(4)
	v_mov_b64_e32 v[132:133], v[204:205]
	v_mov_b64_e32 v[134:135], v[206:207]
	v_mov_b64_e32 v[174:175], v[208:209]
	v_mov_b64_e32 v[176:177], v[210:211]
	v_mov_b64_e32 v[182:183], v[220:221]
	v_mov_b64_e32 v[184:185], v[222:223]
	v_mov_b64_e32 v[186:187], v[224:225]
	v_mov_b64_e32 v[188:189], v[226:227]
	v_lshl_add_u64 v[244:245], v[244:245], 0, v[246:247]
	global_load_dwordx4 v[204:207], v[244:245], off
	global_load_dwordx4 v[208:211], v[244:245], off offset:64
	global_load_dwordx4 v[220:223], v[244:245], off offset:512
	global_load_dwordx4 v[224:227], v[244:245], off offset:576
	v_add_u32_e32 v190, 0x80, v172
	v_ashrrev_i32_e32 v191, 31, v190
	v_lshlrev_b64 v[190:191], 12, v[190:191]
	v_lshl_add_u64 v[190:191], v[138:139], 0, v[190:191]
	v_lshl_add_u64 v[190:191], v[190:191], 0, v[136:137]
	s_waitcnt lgkmcnt(0)
	v_pk_mul_f32 v[134:135], v[134:135], s[6:7] op_sel_hi:[1,0]
	v_pk_mul_f32 v[132:133], v[132:133], s[6:7] op_sel_hi:[1,0]
	v_pk_mul_f32 v[176:177], v[176:177], s[6:7] op_sel_hi:[1,0]
	v_pk_mul_f32 v[174:175], v[174:175], s[6:7] op_sel_hi:[1,0]
	v_pk_mul_f32 v[184:185], v[184:185], s[6:7] op_sel_hi:[1,0]
	v_pk_mul_f32 v[182:183], v[182:183], s[6:7] op_sel_hi:[1,0]
	v_pk_mul_f32 v[188:189], v[188:189], s[6:7] op_sel_hi:[1,0]
	v_pk_mul_f32 v[186:187], v[186:187], s[6:7] op_sel_hi:[1,0]
	v_pk_fma_f32 v[114:115], v[114:115], v[156:157], v[134:135]
	v_pk_fma_f32 v[112:113], v[112:113], v[158:159], v[132:133]
	v_pk_fma_f32 v[82:83], v[82:83], v[160:161], v[176:177]
	v_pk_fma_f32 v[80:81], v[80:81], v[162:163], v[174:175]
	v_pk_fma_f32 v[50:51], v[50:51], v[164:165], v[184:185]
	v_pk_fma_f32 v[48:49], v[48:49], v[166:167], v[182:183]
	v_pk_fma_f32 v[18:19], v[18:19], v[168:169], v[188:189]
	v_pk_fma_f32 v[16:17], v[16:17], v[170:171], v[186:187]
	s_nop 0
	s_waitcnt vmcnt(4)
	v_mov_b64_e32 v[132:133], v[228:229]
	v_mov_b64_e32 v[134:135], v[230:231]
	v_mov_b64_e32 v[174:175], v[232:233]
	v_mov_b64_e32 v[176:177], v[234:235]
	v_mov_b64_e32 v[182:183], v[236:237]
	v_mov_b64_e32 v[184:185], v[238:239]
	v_mov_b64_e32 v[186:187], v[240:241]
	v_mov_b64_e32 v[188:189], v[242:243]
	v_lshl_add_u64 v[244:245], v[244:245], 0, v[246:247]
	global_load_dwordx4 v[228:231], v[244:245], off
	global_load_dwordx4 v[232:235], v[244:245], off offset:64
	global_load_dwordx4 v[236:239], v[244:245], off offset:512
	global_load_dwordx4 v[240:243], v[244:245], off offset:576
	v_add_u32_e32 v190, 0x90, v172
	v_ashrrev_i32_e32 v191, 31, v190
	v_lshlrev_b64 v[190:191], 12, v[190:191]
	v_lshl_add_u64 v[190:191], v[138:139], 0, v[190:191]
	v_lshl_add_u64 v[190:191], v[190:191], 0, v[136:137]
	s_waitcnt lgkmcnt(0)
;     __device__ __forceinline__ bool run(const f32x4 (&v)[2][2][4][2], const Unit& u, int wr, int wc, int fr, int fq, PG8_LAS unsigned char* lds, int wid, int lane) const {
;     ...
;                 float s = 0.f;
; #pragma unroll
;                 for (int bj = 0; bj < 2; ++bj)
; #pragma unroll
;                     for (int n = 0; n < 2; ++n) { const f32x4 x = v[ai][bj][m][n]; s += (x[0] + x[1]) + (x[2] + x[3]); }
;                 s += __shfl_xor(s, 16); s += __shfl_xor(s, 32);
;     __device__ __forceinline__ void fused(f32x4 (&acc)[2][2][4][2], const Unit& u, int wr, int wc, int fr, int fq, PG8_LAS unsigned char* lds, int wid, int lane) const {
;     ...
;         for (int ai = 0; ai < 2; ++ai)
; #pragma unroll
;             for (int m = 0; m < 4; ++m) { const size_t off = (size_t)(u.pm * BM + ai * HALF + wr * 64 + m * 16 + fr) * 1024 + col0;
; #pragma unroll
;                 for (int bj = 0; bj < 2; ++bj)
; #pragma unroll
;                     for (int n = 0; n < 2; ++n) { const f32x4 xv = *(const f32x4*)(xin + off + bj * HALF + n * 16); acc[ai][bj][m][n] = xv * ALPHA_ + acc[ai][bj][m][n]; }
;                 asm volatile("" : "+v"(acc[ai][0][m][0]), "+v"(acc[ai][0][m][1]), "+v"(acc[ai][1][m][0]), "+v"(acc[ai][1][m][1]));
;                 if (m & 1) asm volatile("" ::: "memory"); }
	v_pk_mul_f32 v[134:135], v[134:135], s[6:7] op_sel_hi:[1,0]
	v_pk_mul_f32 v[132:133], v[132:133], s[6:7] op_sel_hi:[1,0]
	v_pk_mul_f32 v[176:177], v[176:177], s[6:7] op_sel_hi:[1,0]
	v_pk_mul_f32 v[174:175], v[174:175], s[6:7] op_sel_hi:[1,0]
	v_pk_mul_f32 v[184:185], v[184:185], s[6:7] op_sel_hi:[1,0]
	v_pk_mul_f32 v[182:183], v[182:183], s[6:7] op_sel_hi:[1,0]
	v_pk_mul_f32 v[188:189], v[188:189], s[6:7] op_sel_hi:[1,0]
	v_pk_mul_f32 v[186:187], v[186:187], s[6:7] op_sel_hi:[1,0]
	v_pk_fma_f32 v[118:119], v[118:119], v[156:157], v[134:135]
	v_pk_fma_f32 v[116:117], v[116:117], v[158:159], v[132:133]
	v_pk_fma_f32 v[86:87], v[86:87], v[160:161], v[176:177]
	v_pk_fma_f32 v[84:85], v[84:85], v[162:163], v[174:175]
	v_pk_fma_f32 v[54:55], v[54:55], v[164:165], v[184:185]
	v_pk_fma_f32 v[52:53], v[52:53], v[166:167], v[182:183]
	v_pk_fma_f32 v[22:23], v[22:23], v[168:169], v[188:189]
	v_pk_fma_f32 v[20:21], v[20:21], v[170:171], v[186:187]
	s_nop 0
	s_waitcnt vmcnt(4)
	v_mov_b64_e32 v[132:133], v[204:205]
	v_mov_b64_e32 v[134:135], v[206:207]
	v_mov_b64_e32 v[174:175], v[208:209]
	v_mov_b64_e32 v[176:177], v[210:211]
	v_mov_b64_e32 v[182:183], v[220:221]
	v_mov_b64_e32 v[184:185], v[222:223]
	v_mov_b64_e32 v[186:187], v[224:225]
	v_mov_b64_e32 v[188:189], v[226:227]
	v_lshl_add_u64 v[244:245], v[244:245], 0, v[246:247]
	global_load_dwordx4 v[204:207], v[244:245], off
	global_load_dwordx4 v[208:211], v[244:245], off offset:64
	global_load_dwordx4 v[220:223], v[244:245], off offset:512
	global_load_dwordx4 v[224:227], v[244:245], off offset:576
	v_add_u32_e32 v190, 0xa0, v172
	v_ashrrev_i32_e32 v191, 31, v190
	v_lshlrev_b64 v[190:191], 12, v[190:191]
	v_lshl_add_u64 v[190:191], v[138:139], 0, v[190:191]
	v_lshl_add_u64 v[190:191], v[190:191], 0, v[136:137]
	s_waitcnt lgkmcnt(0)
	v_pk_mul_f32 v[134:135], v[134:135], s[6:7] op_sel_hi:[1,0]
	v_pk_mul_f32 v[132:133], v[132:133], s[6:7] op_sel_hi:[1,0]
	v_pk_mul_f32 v[176:177], v[176:177], s[6:7] op_sel_hi:[1,0]
	v_pk_mul_f32 v[174:175], v[174:175], s[6:7] op_sel_hi:[1,0]
	v_pk_mul_f32 v[184:185], v[184:185], s[6:7] op_sel_hi:[1,0]
	v_pk_mul_f32 v[182:183], v[182:183], s[6:7] op_sel_hi:[1,0]
	v_pk_mul_f32 v[188:189], v[188:189], s[6:7] op_sel_hi:[1,0]
	v_pk_mul_f32 v[186:187], v[186:187], s[6:7] op_sel_hi:[1,0]
	v_pk_fma_f32 v[122:123], v[122:123], v[156:157], v[134:135]
	v_pk_fma_f32 v[120:121], v[120:121], v[158:159], v[132:133]
	v_pk_fma_f32 v[90:91], v[90:91], v[160:161], v[176:177]
	v_pk_fma_f32 v[88:89], v[88:89], v[162:163], v[174:175]
	v_pk_fma_f32 v[58:59], v[58:59], v[164:165], v[184:185]
	v_pk_fma_f32 v[56:57], v[56:57], v[166:167], v[182:183]
	v_pk_fma_f32 v[26:27], v[26:27], v[168:169], v[188:189]
	v_pk_fma_f32 v[24:25], v[24:25], v[170:171], v[186:187]
	v_mbcnt_hi_u32_b32 v133, -1, v145
	s_nop 0
	s_waitcnt vmcnt(4)
	v_mov_b64_e32 v[174:175], v[228:229]
	v_mov_b64_e32 v[176:177], v[230:231]
	v_mov_b64_e32 v[182:183], v[232:233]
	v_mov_b64_e32 v[184:185], v[234:235]
	v_mov_b64_e32 v[186:187], v[236:237]
	v_mov_b64_e32 v[188:189], v[238:239]
	v_mov_b64_e32 v[190:191], v[240:241]
	v_mov_b64_e32 v[192:193], v[242:243]
	v_and_b32_e32 v134, 64, v133
	v_add_u32_e32 v181, 64, v134
	v_add_u32_e32 v134, 0xb0, v172
	v_ashrrev_i32_e32 v135, 31, v134
	v_lshlrev_b64 v[134:135], 12, v[134:135]
	v_lshl_add_u64 v[134:135], v[138:139], 0, v[134:135]
	v_lshl_add_u64 v[134:135], v[134:135], 0, v[136:137]
	v_mov_b32_e32 v138, v93
	v_mov_b32_e32 v139, v94
	v_pk_add_f32 v[138:139], v[138:139], v[194:195]
	v_xor_b32_e32 v132, 16, v133
	v_add_f32_e32 v194, v138, v139
	v_add_f32_e32 v201, 0, v194
	v_cmp_lt_i32_e32 vcc, v132, v181
	s_waitcnt lgkmcnt(0)
	v_pk_mul_f32 v[172:173], v[176:177], s[6:7] op_sel_hi:[1,0]
	v_pk_mul_f32 v[174:175], v[174:175], s[6:7] op_sel_hi:[1,0]
	v_pk_mul_f32 v[176:177], v[184:185], s[6:7] op_sel_hi:[1,0]
	v_pk_mul_f32 v[182:183], v[182:183], s[6:7] op_sel_hi:[1,0]
	v_pk_mul_f32 v[184:185], v[188:189], s[6:7] op_sel_hi:[1,0]
	v_pk_mul_f32 v[186:187], v[186:187], s[6:7] op_sel_hi:[1,0]
	v_pk_mul_f32 v[188:189], v[192:193], s[6:7] op_sel_hi:[1,0]
	v_pk_mul_f32 v[190:191], v[190:191], s[6:7] op_sel_hi:[1,0]
	v_pk_fma_f32 v[130:131], v[130:131], v[156:157], v[172:173]
	v_pk_fma_f32 v[128:129], v[128:129], v[158:159], v[174:175]
	v_pk_fma_f32 v[98:99], v[98:99], v[160:161], v[176:177]
	v_pk_fma_f32 v[96:97], v[96:97], v[162:163], v[182:183]
	v_pk_fma_f32 v[66:67], v[66:67], v[164:165], v[184:185]
	v_pk_fma_f32 v[64:65], v[64:65], v[166:167], v[186:187]
	v_pk_fma_f32 v[34:35], v[34:35], v[168:169], v[188:189]
	v_pk_fma_f32 v[32:33], v[32:33], v[170:171], v[190:191]
	v_mov_b32_e32 v176, v60
	s_waitcnt vmcnt(0)
;     __device__ __forceinline__ bool run(const f32x4 (&v)[2][2][4][2], const Unit& u, int wr, int wc, int fr, int fq, PG8_LAS unsigned char* lds, int wid, int lane) const {
;     ...
;                 float s = 0.f;
; #pragma unroll
;                 for (int bj = 0; bj < 2; ++bj)
; #pragma unroll
;                     for (int n = 0; n < 2; ++n) { const f32x4 x = v[ai][bj][m][n]; s += (x[0] + x[1]) + (x[2] + x[3]); }
;                 s += __shfl_xor(s, 16); s += __shfl_xor(s, 32);
;                 const float mw = s * (1.0f / 64.0f); float q = 0.f;
; #pragma unroll
;                 for (int bj = 0; bj < 2; ++bj)
; #pragma unroll
;                     for (int n = 0; n < 2; ++n) { const f32x4 d = v[ai][bj][m][n] - mw; q += (d[0] * d[0] + d[1] * d[1]) + (d[2] * d[2] + d[3] * d[3]); }
;                 q += __shfl_xor(q, 16); q += __shfl_xor(q, 32);
;                 if (fq == 0) P[(ai * HALF + wr * 64 + m * 16 + fr) * 4 + wc] = (f32x2v){mw, q};
;     __device__ __forceinline__ void fused(f32x4 (&acc)[2][2][4][2], const Unit& u, int wr, int wc, int fr, int fq, PG8_LAS unsigned char* lds, int wid, int lane) const {
;     ...
;         for (int ai = 0; ai < 2; ++ai)
; #pragma unroll
;             for (int m = 0; m < 4; ++m) { const size_t off = (size_t)(u.pm * BM + ai * HALF + wr * 64 + m * 16 + fr) * 1024 + col0;
; #pragma unroll
;                 for (int bj = 0; bj < 2; ++bj)
; #pragma unroll
;                     for (int n = 0; n < 2; ++n) { const f32x4 xv = *(const f32x4*)(xin + off + bj * HALF + n * 16); acc[ai][bj][m][n] = xv * ALPHA_ + acc[ai][bj][m][n]; }
;                 asm volatile("" : "+v"(acc[ai][0][m][0]), "+v"(acc[ai][0][m][1]), "+v"(acc[ai][1][m][0]), "+v"(acc[ai][1][m][1]));
;                 if (m & 1) asm volatile("" ::: "memory"); }
	v_mov_b64_e32 v[172:173], v[204:205]
	v_mov_b64_e32 v[174:175], v[206:207]
	v_mov_b64_e32 v[182:183], v[208:209]
	v_mov_b64_e32 v[184:185], v[210:211]
	v_mov_b64_e32 v[186:187], v[220:221]
	v_mov_b64_e32 v[188:189], v[222:223]
	v_mov_b64_e32 v[190:191], v[224:225]
	v_mov_b64_e32 v[192:193], v[226:227]
	v_mov_b32_e32 v177, v63
	v_pk_add_f32 v[176:177], v[196:197], v[176:177]
	v_add_f32_e32 v135, v28, v29
	v_pk_add_f32 v[138:139], v[176:177], v[176:177] op_sel_hi:[0,1]
	v_mov_b32_e32 v134, v4
	v_mov_b32_e32 v138, v6
	v_pk_add_f32 v[134:135], v[134:135], v[198:199]
	v_pk_add_f32 v[138:139], v[138:139], v[200:201]
	v_cndmask_b32_e32 v132, v133, v132, vcc
	v_pk_add_f32 v[134:135], v[134:135], v[138:139]
	v_lshlrev_b32_e32 v132, 2, v132
	v_add_f32_e32 v134, v134, v135
	ds_bpermute_b32 v135, v132, v134
	v_xor_b32_e32 v138, 32, v133
	v_cmp_lt_i32_e32 vcc, v138, v181
	s_waitcnt lgkmcnt(0)
	v_add_f32_e32 v134, v134, v135
	v_cndmask_b32_e32 v133, v133, v138, vcc
	v_lshlrev_b32_e32 v133, 2, v133
	ds_bpermute_b32 v135, v133, v134
	s_waitcnt lgkmcnt(0)
	v_add_f32_e32 v135, v134, v135
	v_fmamk_f32 v138, v135, 0xbc800000, v95
	v_fmamk_f32 v176, v135, 0xbc800000, v93
	v_fmamk_f32 v181, v135, 0xbc800000, v63
	v_fmamk_f32 v195, v135, 0xbc800000, v61
	v_fmamk_f32 v134, v135, 0xbc800000, v94
	v_fmamk_f32 v139, v135, 0xbc800000, v92
	v_fmamk_f32 v177, v135, 0xbc800000, v62
	v_fmamk_f32 v194, v135, 0xbc800000, v60
	v_fmamk_f32 v197, v135, 0xbc800000, v31
	v_fmamk_f32 v199, v135, 0xbc800000, v29
	v_mul_f32_e32 v176, v176, v176
	v_mul_f32_e32 v138, v138, v138
	v_mul_f32_e32 v195, v195, v195
	v_mul_f32_e32 v181, v181, v181
	v_fmamk_f32 v196, v135, 0xbc800000, v30
	v_fmamk_f32 v198, v135, 0xbc800000, v28
	v_fmamk_f32 v201, v135, 0xbc800000, v7
	v_fmamk_f32 v203, v135, 0xbc800000, v5
	v_mul_f32_e32 v199, v199, v199
	v_mul_f32_e32 v197, v197, v197
	v_fmac_f32_e32 v176, v139, v139
	v_fmac_f32_e32 v138, v134, v134
	v_fmac_f32_e32 v195, v194, v194
	v_fmac_f32_e32 v181, v177, v177
	v_fmamk_f32 v200, v135, 0xbc800000, v6
	v_fmamk_f32 v202, v135, 0xbc800000, v4
	v_mul_f32_e32 v203, v203, v203
	v_mul_f32_e32 v201, v201, v201
	v_fmac_f32_e32 v199, v198, v198
	v_fmac_f32_e32 v197, v196, v196
	v_add_f32_e32 v134, v176, v138
	v_add_f32_e32 v138, v195, v181
	v_fmac_f32_e32 v203, v202, v202
	v_fmac_f32_e32 v201, v200, v200
	v_add_f32_e32 v139, v199, v197
	v_add_f32_e32 v134, v134, v138
	v_add_f32_e32 v176, v203, v201
	v_add_f32_e32 v134, v139, v134
	v_add_f32_e32 v138, v176, v134
	ds_bpermute_b32 v139, v132, v138
	v_and_b32_e32 v134, 63, v149
	v_cmp_gt_u32_e32 vcc, 16, v134
	s_waitcnt lgkmcnt(0)
	v_add_f32_e32 v138, v138, v139
	ds_bpermute_b32 v139, v133, v138
	s_nop 0
	v_pk_mul_f32 v[174:175], v[174:175], s[6:7] op_sel_hi:[1,0]
	v_pk_mul_f32 v[172:173], v[172:173], s[6:7] op_sel_hi:[1,0]
	v_pk_mul_f32 v[176:177], v[184:185], s[6:7] op_sel_hi:[1,0]
	v_pk_mul_f32 v[182:183], v[182:183], s[6:7] op_sel_hi:[1,0]
	v_pk_mul_f32 v[184:185], v[188:189], s[6:7] op_sel_hi:[1,0]
	v_pk_mul_f32 v[186:187], v[186:187], s[6:7] op_sel_hi:[1,0]
	v_pk_mul_f32 v[188:189], v[192:193], s[6:7] op_sel_hi:[1,0]
	v_pk_mul_f32 v[190:191], v[190:191], s[6:7] op_sel_hi:[1,0]
	v_pk_fma_f32 v[126:127], v[126:127], v[156:157], v[174:175]
	v_pk_fma_f32 v[124:125], v[124:125], v[158:159], v[172:173]
	v_pk_fma_f32 v[106:107], v[106:107], v[160:161], v[176:177]
	v_pk_fma_f32 v[104:105], v[104:105], v[162:163], v[182:183]
	v_pk_fma_f32 v[78:79], v[78:79], v[164:165], v[184:185]
	v_pk_fma_f32 v[76:77], v[76:77], v[166:167], v[186:187]
	v_pk_fma_f32 v[46:47], v[46:47], v[168:169], v[188:189]
	v_pk_fma_f32 v[44:45], v[44:45], v[170:171], v[190:191]
	s_lshl_b32 s6, s21, 3
	s_add_i32 s8, s6, 0
	s_and_saveexec_b64 s[6:7], vcc
	s_cbranch_execz .LBB0_394
	s_lshl_b32 s9, s51, 11
	s_add_i32 s9, s8, s9
	v_mul_f32_e32 v156, 0x3c800000, v135
	v_lshl_add_u32 v135, v151, 5, s9
	s_waitcnt lgkmcnt(0)
	v_add_f32_e32 v157, v138, v139
	ds_write_b64 v135, v[156:157]

;     __device__ __forceinline__ void fused(f32x4 (&acc)[2][2][4][2], const Unit& u, int wr, int wc, int fr, int fq, PG8_LAS unsigned char* lds, int wid, int lane) const {
;     ...
;         const int col0 = u.pn * BM + wc * 32 + 4 * fq; const int b = (u.pm * BM) >> 13; const size_t mo = (size_t)b * 9216;
; #pragma unroll
;         for (int bj = 0; bj < 2; ++bj)
; #pragma unroll
;             for (int n = 0; n < 2; ++n) { const f32x4 gv = (*(const f32x4*)(gate + mo + col0 + bj * HALF + n * 16) + 1.0f) * coef;
; #pragma unroll
;                 for (int ai = 0; ai < 2; ++ai)
; #pragma unroll
;                     for (int m = 0; m < 4; ++m) acc[ai][bj][m][n] = acc[ai][bj][m][n] * gv; }
; #pragma unroll
;         for (int ai = 0; ai < 2; ++ai)
; #pragma unroll
;             for (int m = 0; m < 4; ++m) { const size_t off = (size_t)(u.pm * BM + ai * HALF + wr * 64 + m * 16 + fr) * 1024 + col0;
; #pragma unroll
;                 for (int bj = 0; bj < 2; ++bj)
; #pragma unroll
;                     for (int n = 0; n < 2; ++n) { const f32x4 xv = *(const f32x4*)(xin + off + bj * HALF + n * 16); acc[ai][bj][m][n] = xv * ALPHA_ + acc[ai][bj][m][n]; }
.LBB0_1300:
	s_lshl_b32 s6, s21, 5
	s_lshl_b32 s7, s14, 8
	s_or_b32 s6, s7, s6
	v_lshrrev_b32_e32 v4, 2, v177
	v_and_or_b32 v140, v4, 12, s6
	s_ashr_i32 s6, s46, 5
	s_mul_hi_i32 s7, s6, 0x2400
	s_mulk_i32 s6, 0x2400
	s_lshl_b64 s[16:17], s[6:7], 2
	v_ashrrev_i32_e32 v141, 31, v140
	s_add_u32 s6, s12, s16
	s_addc_u32 s7, s13, s17
	v_lshlrev_b64 v[136:137], 2, v[140:141]
	v_lshl_add_u64 v[4:5], s[6:7], 0, v[136:137]
	s_mov_b64 s[6:7], 0x5000
	v_lshl_add_u64 v[142:143], v[4:5], 0, s[6:7]
	s_movk_i32 s6, 0x5000
	s_lshl_b32 s20, s46, 8
	v_add_co_u32_e32 v146, vcc, s6, v4
	s_add_i32 s6, s20, s57
	v_or_b32_e32 v158, s6, v178
	v_ashrrev_i32_e32 v159, 31, v158
	s_barrier
	v_addc_co_u32_e32 v147, vcc, 0, v5, vcc
	global_load_dwordx4 v[4:7], v[142:143], off offset:64
	global_load_dwordx4 v[148:151], v[142:143], off offset:512
	global_load_dwordx4 v[152:155], v[146:147], off
	global_load_dwordx4 v[180:183], v[142:143], off offset:576
	v_lshlrev_b64 v[142:143], 12, v[158:159]
	s_waitcnt vmcnt(0) lgkmcnt(0)
	v_lshl_add_u64 v[142:143], v[138:139], 0, v[142:143]
	v_lshl_add_u64 v[142:143], v[142:143], 0, v[136:137]
	global_load_dwordx4 v[184:187], v[142:143], off
	global_load_dwordx4 v[188:191], v[142:143], off offset:64
	global_load_dwordx4 v[192:195], v[142:143], off offset:512
	global_load_dwordx4 v[196:199], v[142:143], off offset:576
	v_mov_b32_e32 v242, 0x10000
	v_mov_b32_e32 v243, 0
	v_mov_b32_e32 v244, 0x50000
	v_mov_b32_e32 v245, 0
	v_lshl_add_u64 v[240:241], v[142:143], 0, v[242:243]
	global_load_dwordx4 v[208:211], v[240:241], off
	global_load_dwordx4 v[212:215], v[240:241], off offset:64
	global_load_dwordx4 v[216:219], v[240:241], off offset:512
	global_load_dwordx4 v[220:223], v[240:241], off offset:576
	v_lshl_add_u64 v[240:241], v[240:241], 0, v[242:243]
	global_load_dwordx4 v[224:227], v[240:241], off
	global_load_dwordx4 v[228:231], v[240:241], off offset:64
	global_load_dwordx4 v[232:235], v[240:241], off offset:512
	global_load_dwordx4 v[236:239], v[240:241], off offset:576
	v_or_b32_e32 v146, 16, v158
	v_ashrrev_i32_e32 v147, 31, v146
	s_mov_b32 s6, 0x3f9837f0
	v_lshlrev_b64 v[146:147], 12, v[146:147]
	v_lshl_add_u64 v[146:147], v[138:139], 0, v[146:147]
	v_lshl_add_u64 v[146:147], v[146:147], 0, v[136:137]
	v_pk_add_f32 v[164:165], v[6:7], 1.0 op_sel_hi:[1,0]
	v_pk_add_f32 v[166:167], v[4:5], 1.0 op_sel_hi:[1,0]
	v_pk_add_f32 v[160:161], v[154:155], 1.0 op_sel_hi:[1,0]
	v_pk_add_f32 v[162:163], v[152:153], 1.0 op_sel_hi:[1,0]
	v_pk_add_f32 v[168:169], v[150:151], 1.0 op_sel_hi:[1,0]
	v_pk_add_f32 v[170:171], v[148:149], 1.0 op_sel_hi:[1,0]
	v_pk_add_f32 v[172:173], v[182:183], 1.0 op_sel_hi:[1,0]
	v_pk_add_f32 v[174:175], v[180:181], 1.0 op_sel_hi:[1,0]
	s_waitcnt vmcnt(8) lgkmcnt(0)
	v_pk_mul_f32 v[4:5], v[186:187], s[6:7] op_sel_hi:[1,0]
	v_pk_mul_f32 v[6:7], v[184:185], s[6:7] op_sel_hi:[1,0]
	v_pk_mul_f32 v[148:149], v[190:191], s[6:7] op_sel_hi:[1,0]
	v_pk_mul_f32 v[150:151], v[188:189], s[6:7] op_sel_hi:[1,0]
	v_pk_mul_f32 v[152:153], v[194:195], s[6:7] op_sel_hi:[1,0]
	v_pk_mul_f32 v[154:155], v[192:193], s[6:7] op_sel_hi:[1,0]
	v_pk_mul_f32 v[156:157], v[198:199], s[6:7] op_sel_hi:[1,0]
	v_pk_mul_f32 v[180:181], v[196:197], s[6:7] op_sel_hi:[1,0]
	v_pk_fma_f32 v[94:95], v[94:95], v[160:161], v[4:5]
	v_pk_fma_f32 v[92:93], v[92:93], v[162:163], v[6:7]
	v_pk_fma_f32 v[66:67], v[66:67], v[164:165], v[148:149]
	v_pk_fma_f32 v[64:65], v[64:65], v[166:167], v[150:151]
	v_pk_fma_f32 v[34:35], v[34:35], v[168:169], v[152:153]
	v_pk_fma_f32 v[32:33], v[32:33], v[170:171], v[154:155]
	v_pk_fma_f32 v[6:7], v[134:135], v[172:173], v[156:157]
	v_pk_fma_f32 v[4:5], v[132:133], v[174:175], v[180:181]
	v_or_b32_e32 v148, 32, v158
	s_waitcnt vmcnt(4)
	v_mov_b64_e32 v[132:133], v[208:209]
	v_mov_b64_e32 v[134:135], v[210:211]
	v_mov_b64_e32 v[150:151], v[212:213]
	v_mov_b64_e32 v[152:153], v[214:215]
	v_mov_b64_e32 v[154:155], v[216:217]
	v_mov_b64_e32 v[156:157], v[218:219]
	v_mov_b64_e32 v[180:181], v[220:221]
	v_mov_b64_e32 v[182:183], v[222:223]
	v_lshl_add_u64 v[240:241], v[240:241], 0, v[242:243]
	global_load_dwordx4 v[208:211], v[240:241], off
	global_load_dwordx4 v[212:215], v[240:241], off offset:64
	global_load_dwordx4 v[216:219], v[240:241], off offset:512
	global_load_dwordx4 v[220:223], v[240:241], off offset:576
	v_ashrrev_i32_e32 v149, 31, v148
	v_lshlrev_b64 v[148:149], 12, v[148:149]
	v_lshl_add_u64 v[148:149], v[138:139], 0, v[148:149]
	v_lshl_add_u64 v[148:149], v[148:149], 0, v[136:137]
	v_mov_b32_e32 v196, v65
	v_mov_b32_e32 v197, v66
	v_mov_b32_e32 v198, v64
	v_mov_b32_e32 v199, v67
	v_add_f32_e32 v201, v32, v33
	v_add_f32_e32 v203, v34, v35
	v_mov_b32_e32 v200, v4
	v_mov_b32_e32 v202, v5
	v_mov_b32_e32 v204, v7
	s_waitcnt lgkmcnt(0)
	v_pk_mul_f32 v[134:135], v[134:135], s[6:7] op_sel_hi:[1,0]
	v_pk_mul_f32 v[132:133], v[132:133], s[6:7] op_sel_hi:[1,0]
	v_pk_mul_f32 v[152:153], v[152:153], s[6:7] op_sel_hi:[1,0]
	v_pk_mul_f32 v[150:151], v[150:151], s[6:7] op_sel_hi:[1,0]
	v_pk_mul_f32 v[156:157], v[156:157], s[6:7] op_sel_hi:[1,0]
	v_pk_mul_f32 v[154:155], v[154:155], s[6:7] op_sel_hi:[1,0]
	v_pk_mul_f32 v[182:183], v[182:183], s[6:7] op_sel_hi:[1,0]
	v_pk_mul_f32 v[180:181], v[180:181], s[6:7] op_sel_hi:[1,0]
	v_pk_fma_f32 v[102:103], v[102:103], v[160:161], v[134:135]
	v_pk_fma_f32 v[100:101], v[100:101], v[162:163], v[132:133]
	v_pk_fma_f32 v[70:71], v[70:71], v[164:165], v[152:153]
	v_pk_fma_f32 v[68:69], v[68:69], v[166:167], v[150:151]
	v_pk_fma_f32 v[38:39], v[38:39], v[168:169], v[156:157]
	v_pk_fma_f32 v[36:37], v[36:37], v[170:171], v[154:155]
	v_pk_fma_f32 v[10:11], v[10:11], v[172:173], v[182:183]
	v_pk_fma_f32 v[8:9], v[8:9], v[174:175], v[180:181]
	v_or_b32_e32 v150, 48, v158
	s_waitcnt vmcnt(4)
;     __device__ __forceinline__ void fused(f32x4 (&acc)[2][2][4][2], const Unit& u, int wr, int wc, int fr, int fq, PG8_LAS unsigned char* lds, int wid, int lane) const {
;     ...
;         for (int ai = 0; ai < 2; ++ai)
; #pragma unroll
;             for (int m = 0; m < 4; ++m) { const size_t off = (size_t)(u.pm * BM + ai * HALF + wr * 64 + m * 16 + fr) * 1024 + col0;
; #pragma unroll
;                 for (int bj = 0; bj < 2; ++bj)
; #pragma unroll
;                     for (int n = 0; n < 2; ++n) { const f32x4 xv = *(const f32x4*)(xin + off + bj * HALF + n * 16); acc[ai][bj][m][n] = xv * ALPHA_ + acc[ai][bj][m][n]; }
;                 asm volatile("" : "+v"(acc[ai][0][m][0]), "+v"(acc[ai][0][m][1]), "+v"(acc[ai][1][m][0]), "+v"(acc[ai][1][m][1]));
;                 if (m & 1) asm volatile("" ::: "memory"); }
	v_mov_b64_e32 v[132:133], v[224:225]
	v_mov_b64_e32 v[134:135], v[226:227]
	v_mov_b64_e32 v[152:153], v[228:229]
	v_mov_b64_e32 v[154:155], v[230:231]
	v_mov_b64_e32 v[180:181], v[232:233]
	v_mov_b64_e32 v[182:183], v[234:235]
	v_mov_b64_e32 v[184:185], v[236:237]
	v_mov_b64_e32 v[186:187], v[238:239]
	v_lshl_add_u64 v[240:241], v[240:241], 0, v[244:245]
	global_load_dwordx4 v[224:227], v[240:241], off
	global_load_dwordx4 v[228:231], v[240:241], off offset:64
	global_load_dwordx4 v[232:235], v[240:241], off offset:512
	global_load_dwordx4 v[236:239], v[240:241], off offset:576
	v_ashrrev_i32_e32 v151, 31, v150
	v_lshlrev_b64 v[150:151], 12, v[150:151]
	v_lshl_add_u64 v[150:151], v[138:139], 0, v[150:151]
	v_lshl_add_u64 v[150:151], v[150:151], 0, v[136:137]
	s_waitcnt lgkmcnt(0)
	v_pk_mul_f32 v[134:135], v[134:135], s[6:7] op_sel_hi:[1,0]
	v_pk_mul_f32 v[132:133], v[132:133], s[6:7] op_sel_hi:[1,0]
	v_pk_mul_f32 v[154:155], v[154:155], s[6:7] op_sel_hi:[1,0]
	v_pk_mul_f32 v[152:153], v[152:153], s[6:7] op_sel_hi:[1,0]
	v_pk_mul_f32 v[156:157], v[182:183], s[6:7] op_sel_hi:[1,0]
	v_pk_mul_f32 v[180:181], v[180:181], s[6:7] op_sel_hi:[1,0]
	v_pk_mul_f32 v[182:183], v[186:187], s[6:7] op_sel_hi:[1,0]
	v_pk_mul_f32 v[184:185], v[184:185], s[6:7] op_sel_hi:[1,0]
	v_pk_fma_f32 v[106:107], v[106:107], v[160:161], v[134:135]
	v_pk_fma_f32 v[104:105], v[104:105], v[162:163], v[132:133]
	v_pk_fma_f32 v[74:75], v[74:75], v[164:165], v[154:155]
	v_pk_fma_f32 v[72:73], v[72:73], v[166:167], v[152:153]
	v_pk_fma_f32 v[42:43], v[42:43], v[168:169], v[156:157]
	v_pk_fma_f32 v[40:41], v[40:41], v[170:171], v[180:181]
	v_pk_fma_f32 v[14:15], v[14:15], v[172:173], v[182:183]
	v_pk_fma_f32 v[12:13], v[12:13], v[174:175], v[184:185]
	v_add_u32_e32 v152, 0x80, v158
	s_waitcnt vmcnt(4)
	v_mov_b64_e32 v[132:133], v[208:209]
	v_mov_b64_e32 v[134:135], v[210:211]
	v_mov_b64_e32 v[154:155], v[212:213]
	v_mov_b64_e32 v[156:157], v[214:215]
	v_mov_b64_e32 v[180:181], v[216:217]
	v_mov_b64_e32 v[182:183], v[218:219]
	v_mov_b64_e32 v[184:185], v[220:221]
	v_mov_b64_e32 v[186:187], v[222:223]
	v_lshl_add_u64 v[240:241], v[240:241], 0, v[242:243]
	global_load_dwordx4 v[208:211], v[240:241], off
	global_load_dwordx4 v[212:215], v[240:241], off offset:64
	global_load_dwordx4 v[216:219], v[240:241], off offset:512
	global_load_dwordx4 v[220:223], v[240:241], off offset:576
	v_ashrrev_i32_e32 v153, 31, v152
	v_lshlrev_b64 v[152:153], 12, v[152:153]
	v_lshl_add_u64 v[152:153], v[138:139], 0, v[152:153]
	v_lshl_add_u64 v[152:153], v[152:153], 0, v[136:137]
	s_waitcnt lgkmcnt(0)
	v_pk_mul_f32 v[134:135], v[134:135], s[6:7] op_sel_hi:[1,0]
	v_pk_mul_f32 v[132:133], v[132:133], s[6:7] op_sel_hi:[1,0]
	v_pk_mul_f32 v[156:157], v[156:157], s[6:7] op_sel_hi:[1,0]
	v_pk_mul_f32 v[154:155], v[154:155], s[6:7] op_sel_hi:[1,0]
	v_pk_mul_f32 v[182:183], v[182:183], s[6:7] op_sel_hi:[1,0]
	v_pk_mul_f32 v[180:181], v[180:181], s[6:7] op_sel_hi:[1,0]
	v_pk_mul_f32 v[186:187], v[186:187], s[6:7] op_sel_hi:[1,0]
	v_pk_mul_f32 v[184:185], v[184:185], s[6:7] op_sel_hi:[1,0]
	v_pk_fma_f32 v[114:115], v[114:115], v[160:161], v[134:135]
	v_pk_fma_f32 v[112:113], v[112:113], v[162:163], v[132:133]
	v_pk_fma_f32 v[82:83], v[82:83], v[164:165], v[156:157]
	v_pk_fma_f32 v[80:81], v[80:81], v[166:167], v[154:155]
	v_pk_fma_f32 v[50:51], v[50:51], v[168:169], v[182:183]
	v_pk_fma_f32 v[48:49], v[48:49], v[170:171], v[180:181]
	v_pk_fma_f32 v[18:19], v[18:19], v[172:173], v[186:187]
	v_pk_fma_f32 v[16:17], v[16:17], v[174:175], v[184:185]
	v_add_u32_e32 v154, 0x90, v158
	s_waitcnt vmcnt(4)
	v_mov_b64_e32 v[132:133], v[224:225]
	v_mov_b64_e32 v[134:135], v[226:227]
	v_mov_b64_e32 v[180:181], v[228:229]
	v_mov_b64_e32 v[182:183], v[230:231]
	v_mov_b64_e32 v[184:185], v[232:233]
	v_mov_b64_e32 v[186:187], v[234:235]
	v_mov_b64_e32 v[188:189], v[236:237]
	v_mov_b64_e32 v[190:191], v[238:239]
	v_lshl_add_u64 v[240:241], v[240:241], 0, v[242:243]
	global_load_dwordx4 v[224:227], v[240:241], off
	global_load_dwordx4 v[228:231], v[240:241], off offset:64
	global_load_dwordx4 v[232:235], v[240:241], off offset:512
	global_load_dwordx4 v[236:239], v[240:241], off offset:576
	v_ashrrev_i32_e32 v155, 31, v154
	v_lshlrev_b64 v[154:155], 12, v[154:155]
	v_lshl_add_u64 v[154:155], v[138:139], 0, v[154:155]
	v_lshl_add_u64 v[154:155], v[154:155], 0, v[136:137]
	s_waitcnt lgkmcnt(0)
	v_pk_mul_f32 v[134:135], v[134:135], s[6:7] op_sel_hi:[1,0]
	v_pk_mul_f32 v[132:133], v[132:133], s[6:7] op_sel_hi:[1,0]
	v_pk_mul_f32 v[156:157], v[182:183], s[6:7] op_sel_hi:[1,0]
	v_pk_mul_f32 v[180:181], v[180:181], s[6:7] op_sel_hi:[1,0]
	v_pk_mul_f32 v[182:183], v[186:187], s[6:7] op_sel_hi:[1,0]
	v_pk_mul_f32 v[184:185], v[184:185], s[6:7] op_sel_hi:[1,0]
	v_pk_mul_f32 v[186:187], v[190:191], s[6:7] op_sel_hi:[1,0]
	v_pk_mul_f32 v[188:189], v[188:189], s[6:7] op_sel_hi:[1,0]
	v_pk_fma_f32 v[118:119], v[118:119], v[160:161], v[134:135]
	v_pk_fma_f32 v[116:117], v[116:117], v[162:163], v[132:133]
	v_pk_fma_f32 v[86:87], v[86:87], v[164:165], v[156:157]
	v_pk_fma_f32 v[84:85], v[84:85], v[166:167], v[180:181]
	v_pk_fma_f32 v[54:55], v[54:55], v[168:169], v[182:183]
	v_pk_fma_f32 v[52:53], v[52:53], v[170:171], v[184:185]
	v_pk_fma_f32 v[22:23], v[22:23], v[172:173], v[186:187]
	v_pk_fma_f32 v[20:21], v[20:21], v[174:175], v[188:189]
	v_add_u32_e32 v156, 0xa0, v158
	s_waitcnt vmcnt(4)
;     __device__ __forceinline__ bool run(const f32x4 (&v)[2][2][4][2], const Unit& u, int wr, int wc, int fr, int fq, PG8_LAS unsigned char* lds, int wid, int lane) const {
;     ...
;                 float s = 0.f;
; #pragma unroll
;                 for (int bj = 0; bj < 2; ++bj)
; #pragma unroll
;                     for (int n = 0; n < 2; ++n) { const f32x4 x = v[ai][bj][m][n]; s += (x[0] + x[1]) + (x[2] + x[3]); }
;                 s += __shfl_xor(s, 16); s += __shfl_xor(s, 32);
;     __device__ __forceinline__ void fused(f32x4 (&acc)[2][2][4][2], const Unit& u, int wr, int wc, int fr, int fq, PG8_LAS unsigned char* lds, int wid, int lane) const {
;     ...
;         for (int ai = 0; ai < 2; ++ai)
; #pragma unroll
;             for (int m = 0; m < 4; ++m) { const size_t off = (size_t)(u.pm * BM + ai * HALF + wr * 64 + m * 16 + fr) * 1024 + col0;
; #pragma unroll
;                 for (int bj = 0; bj < 2; ++bj)
; #pragma unroll
;                     for (int n = 0; n < 2; ++n) { const f32x4 xv = *(const f32x4*)(xin + off + bj * HALF + n * 16); acc[ai][bj][m][n] = xv * ALPHA_ + acc[ai][bj][m][n]; }
;                 asm volatile("" : "+v"(acc[ai][0][m][0]), "+v"(acc[ai][0][m][1]), "+v"(acc[ai][1][m][0]), "+v"(acc[ai][1][m][1]));
;                 if (m & 1) asm volatile("" ::: "memory"); }
	v_mov_b64_e32 v[132:133], v[208:209]
	v_mov_b64_e32 v[134:135], v[210:211]
	v_mov_b64_e32 v[180:181], v[212:213]
	v_mov_b64_e32 v[182:183], v[214:215]
	v_mov_b64_e32 v[184:185], v[216:217]
	v_mov_b64_e32 v[186:187], v[218:219]
	v_mov_b64_e32 v[188:189], v[220:221]
	v_mov_b64_e32 v[190:191], v[222:223]
	v_lshl_add_u64 v[240:241], v[240:241], 0, v[242:243]
	global_load_dwordx4 v[208:211], v[240:241], off
	global_load_dwordx4 v[212:215], v[240:241], off offset:64
	global_load_dwordx4 v[216:219], v[240:241], off offset:512
	global_load_dwordx4 v[220:223], v[240:241], off offset:576
	v_ashrrev_i32_e32 v157, 31, v156
	v_lshlrev_b64 v[156:157], 12, v[156:157]
	v_lshl_add_u64 v[156:157], v[138:139], 0, v[156:157]
	v_lshl_add_u64 v[156:157], v[156:157], 0, v[136:137]
	s_waitcnt lgkmcnt(0)
	v_pk_mul_f32 v[134:135], v[134:135], s[6:7] op_sel_hi:[1,0]
	v_pk_mul_f32 v[132:133], v[132:133], s[6:7] op_sel_hi:[1,0]
	v_pk_mul_f32 v[182:183], v[182:183], s[6:7] op_sel_hi:[1,0]
	v_pk_mul_f32 v[180:181], v[180:181], s[6:7] op_sel_hi:[1,0]
	v_pk_mul_f32 v[186:187], v[186:187], s[6:7] op_sel_hi:[1,0]
	v_pk_mul_f32 v[184:185], v[184:185], s[6:7] op_sel_hi:[1,0]
	v_pk_mul_f32 v[190:191], v[190:191], s[6:7] op_sel_hi:[1,0]
	v_pk_mul_f32 v[188:189], v[188:189], s[6:7] op_sel_hi:[1,0]
	v_pk_fma_f32 v[122:123], v[122:123], v[160:161], v[134:135]
	v_pk_fma_f32 v[120:121], v[120:121], v[162:163], v[132:133]
	v_pk_fma_f32 v[90:91], v[90:91], v[164:165], v[182:183]
	v_pk_fma_f32 v[88:89], v[88:89], v[166:167], v[180:181]
	v_pk_fma_f32 v[58:59], v[58:59], v[168:169], v[186:187]
	v_pk_fma_f32 v[56:57], v[56:57], v[170:171], v[184:185]
	v_pk_fma_f32 v[26:27], v[26:27], v[172:173], v[190:191]
	v_pk_fma_f32 v[24:25], v[24:25], v[174:175], v[188:189]
	v_mbcnt_hi_u32_b32 v133, -1, v145
	s_waitcnt vmcnt(4)
	v_mov_b64_e32 v[180:181], v[224:225]
	v_mov_b64_e32 v[182:183], v[226:227]
	v_mov_b64_e32 v[184:185], v[228:229]
	v_mov_b64_e32 v[186:187], v[230:231]
	v_mov_b64_e32 v[188:189], v[232:233]
	v_mov_b64_e32 v[190:191], v[234:235]
	v_mov_b64_e32 v[192:193], v[236:237]
	v_mov_b64_e32 v[194:195], v[238:239]
	v_and_b32_e32 v134, 64, v133
	v_add_u32_e32 v179, 64, v134
	v_add_u32_e32 v134, 0xb0, v158
	v_ashrrev_i32_e32 v135, 31, v134
	v_lshlrev_b64 v[134:135], 12, v[134:135]
	v_lshl_add_u64 v[134:135], v[138:139], 0, v[134:135]
	v_lshl_add_u64 v[158:159], v[134:135], 0, v[136:137]
	v_mov_b32_e32 v134, v93
	v_mov_b32_e32 v135, v94
	v_mov_b32_e32 v138, v92
	v_mov_b32_e32 v139, v95
	v_pk_add_f32 v[134:135], v[134:135], v[138:139]
	v_pk_add_f32 v[138:139], v[196:197], v[198:199]
	v_add_f32_e32 v198, v134, v135
	v_pk_add_f32 v[134:135], v[138:139], v[138:139] op_sel_hi:[0,1]
	v_xor_b32_e32 v132, 16, v133
	v_add_f32_e32 v205, 0, v198
	v_mov_b32_e32 v134, v6
	v_cmp_lt_i32_e32 vcc, v132, v179
	v_pk_add_f32 v[196:197], v[200:201], v[202:203]
	v_pk_add_f32 v[134:135], v[134:135], v[204:205]
	v_cndmask_b32_e32 v132, v133, v132, vcc
	v_pk_add_f32 v[134:135], v[196:197], v[134:135]
	v_lshlrev_b32_e32 v132, 2, v132
	v_add_f32_e32 v134, v134, v135
	ds_bpermute_b32 v135, v132, v134
	v_xor_b32_e32 v138, 32, v133
	v_cmp_lt_i32_e32 vcc, v138, v179
	s_waitcnt lgkmcnt(0)
	v_add_f32_e32 v134, v134, v135
	v_cndmask_b32_e32 v133, v133, v138, vcc
	v_lshlrev_b32_e32 v133, 2, v133
	ds_bpermute_b32 v135, v133, v134
	s_waitcnt lgkmcnt(0)
;     __device__ __forceinline__ bool run(const f32x4 (&v)[2][2][4][2], const Unit& u, int wr, int wc, int fr, int fq, PG8_LAS unsigned char* lds, int wid, int lane) const {
;     ...
;                 const float mw = s * (1.0f / 64.0f); float q = 0.f;
; #pragma unroll
;                 for (int bj = 0; bj < 2; ++bj)
; #pragma unroll
;                     for (int n = 0; n < 2; ++n) { const f32x4 d = v[ai][bj][m][n] - mw; q += (d[0] * d[0] + d[1] * d[1]) + (d[2] * d[2] + d[3] * d[3]); }
;                 q += __shfl_xor(q, 16); q += __shfl_xor(q, 32);
;                 if (fq == 0) P[(ai * HALF + wr * 64 + m * 16 + fr) * 4 + wc] = (f32x2v){mw, q};
;     __device__ __forceinline__ void fused(f32x4 (&acc)[2][2][4][2], const Unit& u, int wr, int wc, int fr, int fq, PG8_LAS unsigned char* lds, int wid, int lane) const {
;     ...
;         for (int ai = 0; ai < 2; ++ai)
; #pragma unroll
;             for (int m = 0; m < 4; ++m) { const size_t off = (size_t)(u.pm * BM + ai * HALF + wr * 64 + m * 16 + fr) * 1024 + col0;
; #pragma unroll
;                 for (int bj = 0; bj < 2; ++bj)
; #pragma unroll
;                     for (int n = 0; n < 2; ++n) { const f32x4 xv = *(const f32x4*)(xin + off + bj * HALF + n * 16); acc[ai][bj][m][n] = xv * ALPHA_ + acc[ai][bj][m][n]; }
;                 asm volatile("" : "+v"(acc[ai][0][m][0]), "+v"(acc[ai][0][m][1]), "+v"(acc[ai][1][m][0]), "+v"(acc[ai][1][m][1]));
;                 if (m & 1) asm volatile("" ::: "memory"); }
	v_add_f32_e32 v135, v134, v135
	v_fmamk_f32 v138, v135, 0xbc800000, v95
	v_fmamk_f32 v179, v135, 0xbc800000, v93
	v_fmamk_f32 v197, v135, 0xbc800000, v67
	v_fmamk_f32 v199, v135, 0xbc800000, v65
	v_fmamk_f32 v134, v135, 0xbc800000, v94
	v_fmamk_f32 v139, v135, 0xbc800000, v92
	v_fmamk_f32 v196, v135, 0xbc800000, v66
	v_fmamk_f32 v198, v135, 0xbc800000, v64
	v_fmamk_f32 v201, v135, 0xbc800000, v35
	v_fmamk_f32 v203, v135, 0xbc800000, v33
	v_mul_f32_e32 v179, v179, v179
	v_mul_f32_e32 v138, v138, v138
	v_mul_f32_e32 v199, v199, v199
	v_mul_f32_e32 v197, v197, v197
	v_fmamk_f32 v200, v135, 0xbc800000, v34
	v_fmamk_f32 v202, v135, 0xbc800000, v32
	v_fmamk_f32 v205, v135, 0xbc800000, v7
	v_fmamk_f32 v207, v135, 0xbc800000, v5
	v_mul_f32_e32 v203, v203, v203
	v_mul_f32_e32 v201, v201, v201
	v_fmac_f32_e32 v179, v139, v139
	v_fmac_f32_e32 v138, v134, v134
	v_fmac_f32_e32 v199, v198, v198
	v_fmac_f32_e32 v197, v196, v196
	v_fmamk_f32 v204, v135, 0xbc800000, v6
	v_fmamk_f32 v206, v135, 0xbc800000, v4
	v_mul_f32_e32 v207, v207, v207
	v_mul_f32_e32 v205, v205, v205
	v_fmac_f32_e32 v203, v202, v202
	v_fmac_f32_e32 v201, v200, v200
	v_add_f32_e32 v134, v179, v138
	v_add_f32_e32 v138, v199, v197
	v_fmac_f32_e32 v207, v206, v206
	v_fmac_f32_e32 v205, v204, v204
	v_add_f32_e32 v139, v203, v201
	v_add_f32_e32 v134, v134, v138
	v_add_f32_e32 v179, v207, v205
	s_nop 0
	v_pk_mul_f32 v[182:183], v[182:183], s[6:7] op_sel_hi:[1,0]
	v_pk_mul_f32 v[180:181], v[180:181], s[6:7] op_sel_hi:[1,0]
	v_pk_mul_f32 v[186:187], v[186:187], s[6:7] op_sel_hi:[1,0]
	v_pk_mul_f32 v[184:185], v[184:185], s[6:7] op_sel_hi:[1,0]
	v_pk_mul_f32 v[190:191], v[190:191], s[6:7] op_sel_hi:[1,0]
	v_pk_mul_f32 v[188:189], v[188:189], s[6:7] op_sel_hi:[1,0]
	v_pk_mul_f32 v[194:195], v[194:195], s[6:7] op_sel_hi:[1,0]
	v_pk_mul_f32 v[192:193], v[192:193], s[6:7] op_sel_hi:[1,0]
	v_pk_fma_f32 v[126:127], v[126:127], v[160:161], v[182:183]
	v_pk_fma_f32 v[124:125], v[124:125], v[162:163], v[180:181]
	v_pk_fma_f32 v[98:99], v[98:99], v[164:165], v[186:187]
	v_pk_fma_f32 v[96:97], v[96:97], v[166:167], v[184:185]
	v_pk_fma_f32 v[62:63], v[62:63], v[168:169], v[190:191]
	v_pk_fma_f32 v[60:61], v[60:61], v[170:171], v[188:189]
	v_pk_fma_f32 v[30:31], v[30:31], v[172:173], v[194:195]
	v_pk_fma_f32 v[28:29], v[28:29], v[174:175], v[192:193]
	v_add_f32_e32 v134, v139, v134
	s_waitcnt vmcnt(0)
	v_mov_b64_e32 v[180:181], v[208:209]
	v_mov_b64_e32 v[182:183], v[210:211]
	v_mov_b64_e32 v[184:185], v[212:213]
	v_mov_b64_e32 v[186:187], v[214:215]
	v_mov_b64_e32 v[188:189], v[216:217]
	v_mov_b64_e32 v[190:191], v[218:219]
	v_mov_b64_e32 v[192:193], v[220:221]
	v_mov_b64_e32 v[194:195], v[222:223]
	v_add_f32_e32 v138, v179, v134
	ds_bpermute_b32 v139, v132, v138
	v_and_b32_e32 v134, 63, v177
	v_cmp_gt_u32_e32 vcc, 16, v134
	s_waitcnt lgkmcnt(0)
	v_add_f32_e32 v138, v138, v139
	ds_bpermute_b32 v139, v133, v138
	s_nop 0
	v_pk_mul_f32 v[182:183], v[182:183], s[6:7] op_sel_hi:[1,0]
	v_pk_mul_f32 v[180:181], v[180:181], s[6:7] op_sel_hi:[1,0]
	v_pk_mul_f32 v[186:187], v[186:187], s[6:7] op_sel_hi:[1,0]
	v_pk_mul_f32 v[184:185], v[184:185], s[6:7] op_sel_hi:[1,0]
	v_pk_mul_f32 v[190:191], v[190:191], s[6:7] op_sel_hi:[1,0]
	v_pk_mul_f32 v[188:189], v[188:189], s[6:7] op_sel_hi:[1,0]
	v_pk_mul_f32 v[194:195], v[194:195], s[6:7] op_sel_hi:[1,0]
	v_pk_mul_f32 v[192:193], v[192:193], s[6:7] op_sel_hi:[1,0]
	v_pk_fma_f32 v[130:131], v[130:131], v[160:161], v[182:183]
	v_pk_fma_f32 v[128:129], v[128:129], v[162:163], v[180:181]
	v_pk_fma_f32 v[110:111], v[110:111], v[164:165], v[186:187]
	v_pk_fma_f32 v[108:109], v[108:109], v[166:167], v[184:185]
	v_pk_fma_f32 v[78:79], v[78:79], v[168:169], v[190:191]
	v_pk_fma_f32 v[76:77], v[76:77], v[170:171], v[188:189]
	v_pk_fma_f32 v[46:47], v[46:47], v[172:173], v[194:195]
	v_pk_fma_f32 v[44:45], v[44:45], v[174:175], v[192:193]
	s_lshl_b32 s6, s21, 3
	s_add_i32 s8, s6, 0
	s_and_saveexec_b64 s[6:7], vcc
	s_cbranch_execz .LBB0_1302
	s_lshl_b32 s9, s47, 11
	s_add_i32 s9, s8, s9
	v_mul_f32_e32 v160, 0x3c800000, v135
	v_lshl_add_u32 v135, v178, 5, s9
	s_waitcnt lgkmcnt(0)
	v_add_f32_e32 v161, v138, v139
	ds_write_b64 v135, v[160:161]

;     __device__ __forceinline__ void fused(f32x4 (&acc)[2][2][4][2], const Unit& u, int wr, int wc, int fr, int fq, PG8_LAS unsigned char* lds, int wid, int lane) const {
;     ...
;         const int col0 = u.pn * BM + wc * 32 + 4 * fq; const int b = (u.pm * BM) >> 13; const size_t mo = (size_t)b * 9216;
; #pragma unroll
;         for (int bj = 0; bj < 2; ++bj)
; #pragma unroll
;             for (int n = 0; n < 2; ++n) { const f32x4 gv = (*(const f32x4*)(gate + mo + col0 + bj * HALF + n * 16) + 1.0f) * coef;
; #pragma unroll
;                 for (int ai = 0; ai < 2; ++ai)
; #pragma unroll
;                     for (int m = 0; m < 4; ++m) acc[ai][bj][m][n] = acc[ai][bj][m][n] * gv; }
; #pragma unroll
;         for (int ai = 0; ai < 2; ++ai)
; #pragma unroll
;             for (int m = 0; m < 4; ++m) { const size_t off = (size_t)(u.pm * BM + ai * HALF + wr * 64 + m * 16 + fr) * 1024 + col0;
; #pragma unroll
;                 for (int bj = 0; bj < 2; ++bj)
; #pragma unroll
;                     for (int n = 0; n < 2; ++n) { const f32x4 xv = *(const f32x4*)(xin + off + bj * HALF + n * 16); acc[ai][bj][m][n] = xv * ALPHA_ + acc[ai][bj][m][n]; }
.LBB0_1491:
	s_lshl_b32 s0, s42, 5
	s_lshl_b32 s1, s10, 8
	s_or_b32 s0, s1, s0
	v_lshrrev_b32_e32 v4, 2, v144
	v_and_or_b32 v138, v4, 12, s0
	s_ashr_i32 s0, s41, 5
	s_mul_hi_i32 s1, s0, 0x9000
	s_mul_i32 s0, s0, 0x9000
	v_ashrrev_i32_e32 v139, 31, v138
	s_add_u32 s0, s8, s0
	s_addc_u32 s1, s9, s1
	v_lshlrev_b64 v[140:141], 2, v[138:139]
	v_lshl_add_u64 v[142:143], s[0:1], 0, v[140:141]
	s_mov_b32 s2, 0x8000
	s_mov_b64 s[0:1], 0x8000
	v_add_co_u32_e32 v4, vcc, s2, v142
	s_lshl_b32 s16, s41, 8
	s_nop 0
	v_addc_co_u32_e32 v5, vcc, 0, v143, vcc
	v_lshl_add_u64 v[142:143], v[142:143], 0, s[0:1]
	s_add_i32 s0, s16, s53
	v_or_b32_e32 v160, s0, v163
	v_ashrrev_i32_e32 v161, 31, v160
	s_barrier
	global_load_dwordx4 v[4:7], v[4:5], off
	s_nop 0
	global_load_dwordx4 v[146:149], v[142:143], off offset:64
	global_load_dwordx4 v[150:153], v[142:143], off offset:512
	global_load_dwordx4 v[154:157], v[142:143], off offset:576
	v_lshlrev_b64 v[142:143], 12, v[160:161]
	s_waitcnt vmcnt(0) lgkmcnt(0)
	v_lshl_add_u64 v[142:143], v[136:137], 0, v[142:143]
	v_lshl_add_u64 v[142:143], v[142:143], 0, v[140:141]
	global_load_dwordx4 v[164:167], v[142:143], off
	global_load_dwordx4 v[168:171], v[142:143], off offset:64
	global_load_dwordx4 v[172:175], v[142:143], off offset:512
	global_load_dwordx4 v[176:179], v[142:143], off offset:576
	v_mov_b32_e32 v226, 0x10000
	v_mov_b32_e32 v227, 0
	v_mov_b32_e32 v228, 0x50000
	v_mov_b32_e32 v229, 0
	v_lshl_add_u64 v[224:225], v[142:143], 0, v[226:227]
	global_load_dwordx4 v[192:195], v[224:225], off
	global_load_dwordx4 v[196:199], v[224:225], off offset:64
	global_load_dwordx4 v[200:203], v[224:225], off offset:512
	global_load_dwordx4 v[204:207], v[224:225], off offset:576
	v_lshl_add_u64 v[224:225], v[224:225], 0, v[226:227]
	global_load_dwordx4 v[208:211], v[224:225], off
	global_load_dwordx4 v[212:215], v[224:225], off offset:64
	global_load_dwordx4 v[216:219], v[224:225], off offset:512
	global_load_dwordx4 v[220:223], v[224:225], off offset:576
	v_or_b32_e32 v142, 16, v160
	v_ashrrev_i32_e32 v143, 31, v142
	v_lshlrev_b64 v[142:143], 12, v[142:143]
	s_mov_b32 s0, 0x3f9837f0
	v_lshl_add_u64 v[142:143], v[136:137], 0, v[142:143]
	v_lshl_add_u64 v[180:181], v[142:143], 0, v[140:141]
	v_pk_add_f32 v[148:149], v[148:149], 1.0 op_sel_hi:[1,0]
	v_pk_add_f32 v[6:7], v[6:7], 1.0 op_sel_hi:[1,0]
	v_pk_add_f32 v[4:5], v[4:5], 1.0 op_sel_hi:[1,0]
	v_pk_add_f32 v[158:159], v[146:147], 1.0 op_sel_hi:[1,0]
	v_pk_add_f32 v[152:153], v[152:153], 1.0 op_sel_hi:[1,0]
	v_pk_add_f32 v[182:183], v[150:151], 1.0 op_sel_hi:[1,0]
	v_pk_add_f32 v[156:157], v[156:157], 1.0 op_sel_hi:[1,0]
	v_pk_add_f32 v[184:185], v[154:155], 1.0 op_sel_hi:[1,0]
	v_pk_mul_f32 v[142:143], v[6:7], 0.5 op_sel_hi:[1,0]
	v_pk_mul_f32 v[146:147], v[4:5], 0.5 op_sel_hi:[1,0]
	v_pk_mul_f32 v[148:149], v[148:149], 0.5 op_sel_hi:[1,0]
	v_pk_mul_f32 v[150:151], v[158:159], 0.5 op_sel_hi:[1,0]
	v_pk_mul_f32 v[152:153], v[152:153], 0.5 op_sel_hi:[1,0]
	v_pk_mul_f32 v[154:155], v[182:183], 0.5 op_sel_hi:[1,0]
	v_pk_mul_f32 v[156:157], v[156:157], 0.5 op_sel_hi:[1,0]
	v_pk_mul_f32 v[158:159], v[184:185], 0.5 op_sel_hi:[1,0]
	s_waitcnt vmcnt(8) lgkmcnt(0)
	v_pk_mul_f32 v[4:5], v[166:167], s[0:1] op_sel_hi:[1,0]
	v_pk_mul_f32 v[6:7], v[164:165], s[0:1] op_sel_hi:[1,0]
	v_pk_mul_f32 v[164:165], v[170:171], s[0:1] op_sel_hi:[1,0]
	v_pk_mul_f32 v[166:167], v[168:169], s[0:1] op_sel_hi:[1,0]
	v_pk_mul_f32 v[168:169], v[174:175], s[0:1] op_sel_hi:[1,0]
	v_pk_mul_f32 v[170:171], v[172:173], s[0:1] op_sel_hi:[1,0]
	v_pk_mul_f32 v[172:173], v[178:179], s[0:1] op_sel_hi:[1,0]
	v_pk_mul_f32 v[174:175], v[176:177], s[0:1] op_sel_hi:[1,0]
	v_pk_fma_f32 v[82:83], v[82:83], v[142:143], v[4:5]
	v_pk_fma_f32 v[80:81], v[80:81], v[146:147], v[6:7]
	v_pk_fma_f32 v[46:47], v[46:47], v[148:149], v[164:165]
	v_pk_fma_f32 v[44:45], v[44:45], v[150:151], v[166:167]
	v_pk_fma_f32 v[22:23], v[22:23], v[152:153], v[168:169]
	v_pk_fma_f32 v[20:21], v[20:21], v[154:155], v[170:171]
	v_pk_fma_f32 v[6:7], v[134:135], v[156:157], v[172:173]
	v_pk_fma_f32 v[4:5], v[132:133], v[158:159], v[174:175]
	v_or_b32_e32 v176, 32, v160
	s_waitcnt vmcnt(4)
	v_mov_b64_e32 v[132:133], v[192:193]
	v_mov_b64_e32 v[134:135], v[194:195]
	v_mov_b64_e32 v[164:165], v[196:197]
	v_mov_b64_e32 v[166:167], v[198:199]
	v_mov_b64_e32 v[168:169], v[200:201]
	v_mov_b64_e32 v[170:171], v[202:203]
	v_mov_b64_e32 v[172:173], v[204:205]
	v_mov_b64_e32 v[174:175], v[206:207]
	v_lshl_add_u64 v[224:225], v[224:225], 0, v[226:227]
	global_load_dwordx4 v[192:195], v[224:225], off
	global_load_dwordx4 v[196:199], v[224:225], off offset:64
	global_load_dwordx4 v[200:203], v[224:225], off offset:512
	global_load_dwordx4 v[204:207], v[224:225], off offset:576
	v_ashrrev_i32_e32 v177, 31, v176
	v_lshlrev_b64 v[176:177], 12, v[176:177]
	v_lshl_add_u64 v[176:177], v[136:137], 0, v[176:177]
	v_lshl_add_u64 v[176:177], v[176:177], 0, v[140:141]
	v_mov_b32_e32 v161, v82
	v_mov_b32_e32 v180, v80
	v_mov_b32_e32 v181, v83
	v_mov_b32_e32 v182, v45
	v_mov_b32_e32 v183, v46
	v_mov_b32_e32 v184, v44
	v_mov_b32_e32 v185, v47
	v_add_f32_e32 v187, v22, v23
	v_mov_b32_e32 v186, v5
	v_mov_b32_e32 v188, v7
	s_waitcnt lgkmcnt(0)
;     __device__ __forceinline__ void fused(f32x4 (&acc)[2][2][4][2], const Unit& u, int wr, int wc, int fr, int fq, PG8_LAS unsigned char* lds, int wid, int lane) const {
;     ...
;         for (int ai = 0; ai < 2; ++ai)
; #pragma unroll
;             for (int m = 0; m < 4; ++m) { const size_t off = (size_t)(u.pm * BM + ai * HALF + wr * 64 + m * 16 + fr) * 1024 + col0;
; #pragma unroll
;                 for (int bj = 0; bj < 2; ++bj)
; #pragma unroll
;                     for (int n = 0; n < 2; ++n) { const f32x4 xv = *(const f32x4*)(xin + off + bj * HALF + n * 16); acc[ai][bj][m][n] = xv * ALPHA_ + acc[ai][bj][m][n]; }
;                 asm volatile("" : "+v"(acc[ai][0][m][0]), "+v"(acc[ai][0][m][1]), "+v"(acc[ai][1][m][0]), "+v"(acc[ai][1][m][1]));
;                 if (m & 1) asm volatile("" ::: "memory"); }
	v_pk_mul_f32 v[134:135], v[134:135], s[0:1] op_sel_hi:[1,0]
	v_pk_mul_f32 v[132:133], v[132:133], s[0:1] op_sel_hi:[1,0]
	v_pk_mul_f32 v[166:167], v[166:167], s[0:1] op_sel_hi:[1,0]
	v_pk_mul_f32 v[164:165], v[164:165], s[0:1] op_sel_hi:[1,0]
	v_pk_mul_f32 v[170:171], v[170:171], s[0:1] op_sel_hi:[1,0]
	v_pk_mul_f32 v[168:169], v[168:169], s[0:1] op_sel_hi:[1,0]
	v_pk_mul_f32 v[174:175], v[174:175], s[0:1] op_sel_hi:[1,0]
	v_pk_mul_f32 v[172:173], v[172:173], s[0:1] op_sel_hi:[1,0]
	v_pk_fma_f32 v[90:91], v[90:91], v[142:143], v[134:135]
	v_pk_fma_f32 v[88:89], v[88:89], v[146:147], v[132:133]
	v_pk_fma_f32 v[58:59], v[58:59], v[148:149], v[166:167]
	v_pk_fma_f32 v[56:57], v[56:57], v[150:151], v[164:165]
	v_pk_fma_f32 v[30:31], v[30:31], v[152:153], v[170:171]
	v_pk_fma_f32 v[28:29], v[28:29], v[154:155], v[168:169]
	v_pk_fma_f32 v[10:11], v[10:11], v[156:157], v[174:175]
	v_pk_fma_f32 v[8:9], v[8:9], v[158:159], v[172:173]
	s_nop 0
	s_waitcnt vmcnt(4)
	v_mov_b64_e32 v[132:133], v[208:209]
	v_mov_b64_e32 v[134:135], v[210:211]
	v_mov_b64_e32 v[164:165], v[212:213]
	v_mov_b64_e32 v[166:167], v[214:215]
	v_mov_b64_e32 v[168:169], v[216:217]
	v_mov_b64_e32 v[170:171], v[218:219]
	v_mov_b64_e32 v[172:173], v[220:221]
	v_mov_b64_e32 v[174:175], v[222:223]
	v_lshl_add_u64 v[224:225], v[224:225], 0, v[228:229]
	global_load_dwordx4 v[208:211], v[224:225], off
	global_load_dwordx4 v[212:215], v[224:225], off offset:64
	global_load_dwordx4 v[216:219], v[224:225], off offset:512
	global_load_dwordx4 v[220:223], v[224:225], off offset:576
	v_or_b32_e32 v176, 48, v160
	v_ashrrev_i32_e32 v177, 31, v176
	v_lshlrev_b64 v[176:177], 12, v[176:177]
	v_lshl_add_u64 v[176:177], v[136:137], 0, v[176:177]
	v_lshl_add_u64 v[176:177], v[176:177], 0, v[140:141]
	s_waitcnt lgkmcnt(0)
	v_pk_mul_f32 v[134:135], v[134:135], s[0:1] op_sel_hi:[1,0]
	v_pk_mul_f32 v[132:133], v[132:133], s[0:1] op_sel_hi:[1,0]
	v_pk_mul_f32 v[166:167], v[166:167], s[0:1] op_sel_hi:[1,0]
	v_pk_mul_f32 v[164:165], v[164:165], s[0:1] op_sel_hi:[1,0]
	v_pk_mul_f32 v[170:171], v[170:171], s[0:1] op_sel_hi:[1,0]
	v_pk_mul_f32 v[168:169], v[168:169], s[0:1] op_sel_hi:[1,0]
	v_pk_mul_f32 v[174:175], v[174:175], s[0:1] op_sel_hi:[1,0]
	v_pk_mul_f32 v[172:173], v[172:173], s[0:1] op_sel_hi:[1,0]
	v_pk_fma_f32 v[102:103], v[102:103], v[142:143], v[134:135]
	v_pk_fma_f32 v[100:101], v[100:101], v[146:147], v[132:133]
	v_pk_fma_f32 v[70:71], v[70:71], v[148:149], v[166:167]
	v_pk_fma_f32 v[68:69], v[68:69], v[150:151], v[164:165]
	v_pk_fma_f32 v[38:39], v[38:39], v[152:153], v[170:171]
	v_pk_fma_f32 v[36:37], v[36:37], v[154:155], v[168:169]
	v_pk_fma_f32 v[14:15], v[14:15], v[156:157], v[174:175]
	v_pk_fma_f32 v[12:13], v[12:13], v[158:159], v[172:173]
	s_nop 0
	s_waitcnt vmcnt(4)
	v_mov_b64_e32 v[132:133], v[192:193]
	v_mov_b64_e32 v[134:135], v[194:195]
	v_mov_b64_e32 v[164:165], v[196:197]
	v_mov_b64_e32 v[166:167], v[198:199]
	v_mov_b64_e32 v[168:169], v[200:201]
	v_mov_b64_e32 v[170:171], v[202:203]
	v_mov_b64_e32 v[172:173], v[204:205]
	v_mov_b64_e32 v[174:175], v[206:207]
	v_lshl_add_u64 v[224:225], v[224:225], 0, v[226:227]
	global_load_dwordx4 v[192:195], v[224:225], off
	global_load_dwordx4 v[196:199], v[224:225], off offset:64
	global_load_dwordx4 v[200:203], v[224:225], off offset:512
	global_load_dwordx4 v[204:207], v[224:225], off offset:576
	v_add_u32_e32 v176, 0x80, v160
	v_ashrrev_i32_e32 v177, 31, v176
	v_lshlrev_b64 v[176:177], 12, v[176:177]
	v_lshl_add_u64 v[176:177], v[136:137], 0, v[176:177]
	v_lshl_add_u64 v[176:177], v[176:177], 0, v[140:141]
	s_waitcnt lgkmcnt(0)
	v_pk_mul_f32 v[134:135], v[134:135], s[0:1] op_sel_hi:[1,0]
	v_pk_mul_f32 v[132:133], v[132:133], s[0:1] op_sel_hi:[1,0]
	v_pk_mul_f32 v[166:167], v[166:167], s[0:1] op_sel_hi:[1,0]
	v_pk_mul_f32 v[164:165], v[164:165], s[0:1] op_sel_hi:[1,0]
	v_pk_mul_f32 v[170:171], v[170:171], s[0:1] op_sel_hi:[1,0]
	v_pk_mul_f32 v[168:169], v[168:169], s[0:1] op_sel_hi:[1,0]
	v_pk_mul_f32 v[174:175], v[174:175], s[0:1] op_sel_hi:[1,0]
	v_pk_mul_f32 v[172:173], v[172:173], s[0:1] op_sel_hi:[1,0]
	v_pk_fma_f32 v[106:107], v[106:107], v[142:143], v[134:135]
	v_pk_fma_f32 v[104:105], v[104:105], v[146:147], v[132:133]
	v_pk_fma_f32 v[74:75], v[74:75], v[148:149], v[166:167]
	v_pk_fma_f32 v[72:73], v[72:73], v[150:151], v[164:165]
	v_pk_fma_f32 v[42:43], v[42:43], v[152:153], v[170:171]
	v_pk_fma_f32 v[40:41], v[40:41], v[154:155], v[168:169]
	v_pk_fma_f32 v[18:19], v[18:19], v[156:157], v[174:175]
	v_pk_fma_f32 v[16:17], v[16:17], v[158:159], v[172:173]
	s_nop 0
	s_waitcnt vmcnt(4)
	v_mov_b64_e32 v[132:133], v[208:209]
	v_mov_b64_e32 v[134:135], v[210:211]
	v_mov_b64_e32 v[164:165], v[212:213]
	v_mov_b64_e32 v[166:167], v[214:215]
	v_mov_b64_e32 v[168:169], v[216:217]
	v_mov_b64_e32 v[170:171], v[218:219]
	v_mov_b64_e32 v[172:173], v[220:221]
	v_mov_b64_e32 v[174:175], v[222:223]
	v_lshl_add_u64 v[224:225], v[224:225], 0, v[226:227]
	global_load_dwordx4 v[208:211], v[224:225], off
	global_load_dwordx4 v[212:215], v[224:225], off offset:64
	global_load_dwordx4 v[216:219], v[224:225], off offset:512
	global_load_dwordx4 v[220:223], v[224:225], off offset:576
	v_add_u32_e32 v176, 0x90, v160
	v_ashrrev_i32_e32 v177, 31, v176
	v_lshlrev_b64 v[176:177], 12, v[176:177]
	v_lshl_add_u64 v[176:177], v[136:137], 0, v[176:177]
	v_lshl_add_u64 v[176:177], v[176:177], 0, v[140:141]
	s_waitcnt lgkmcnt(0)
;     __device__ __forceinline__ bool run(const f32x4 (&v)[2][2][4][2], const Unit& u, int wr, int wc, int fr, int fq, PG8_LAS unsigned char* lds, int wid, int lane) const {
;     ...
;                 float s = 0.f;
; #pragma unroll
;                 for (int bj = 0; bj < 2; ++bj)
; #pragma unroll
;                     for (int n = 0; n < 2; ++n) { const f32x4 x = v[ai][bj][m][n]; s += (x[0] + x[1]) + (x[2] + x[3]); }
;                 s += __shfl_xor(s, 16); s += __shfl_xor(s, 32);
;     __device__ __forceinline__ void fused(f32x4 (&acc)[2][2][4][2], const Unit& u, int wr, int wc, int fr, int fq, PG8_LAS unsigned char* lds, int wid, int lane) const {
;     ...
;         for (int ai = 0; ai < 2; ++ai)
; #pragma unroll
;             for (int m = 0; m < 4; ++m) { const size_t off = (size_t)(u.pm * BM + ai * HALF + wr * 64 + m * 16 + fr) * 1024 + col0;
; #pragma unroll
;                 for (int bj = 0; bj < 2; ++bj)
; #pragma unroll
;                     for (int n = 0; n < 2; ++n) { const f32x4 xv = *(const f32x4*)(xin + off + bj * HALF + n * 16); acc[ai][bj][m][n] = xv * ALPHA_ + acc[ai][bj][m][n]; }
;                 asm volatile("" : "+v"(acc[ai][0][m][0]), "+v"(acc[ai][0][m][1]), "+v"(acc[ai][1][m][0]), "+v"(acc[ai][1][m][1]));
;                 if (m & 1) asm volatile("" ::: "memory"); }
	v_pk_mul_f32 v[134:135], v[134:135], s[0:1] op_sel_hi:[1,0]
	v_pk_mul_f32 v[132:133], v[132:133], s[0:1] op_sel_hi:[1,0]
	v_pk_mul_f32 v[166:167], v[166:167], s[0:1] op_sel_hi:[1,0]
	v_pk_mul_f32 v[164:165], v[164:165], s[0:1] op_sel_hi:[1,0]
	v_pk_mul_f32 v[170:171], v[170:171], s[0:1] op_sel_hi:[1,0]
	v_pk_mul_f32 v[168:169], v[168:169], s[0:1] op_sel_hi:[1,0]
	v_pk_mul_f32 v[174:175], v[174:175], s[0:1] op_sel_hi:[1,0]
	v_pk_mul_f32 v[172:173], v[172:173], s[0:1] op_sel_hi:[1,0]
	v_pk_fma_f32 v[114:115], v[114:115], v[142:143], v[134:135]
	v_pk_fma_f32 v[112:113], v[112:113], v[146:147], v[132:133]
	v_pk_fma_f32 v[86:87], v[86:87], v[148:149], v[166:167]
	v_pk_fma_f32 v[84:85], v[84:85], v[150:151], v[164:165]
	v_pk_fma_f32 v[54:55], v[54:55], v[152:153], v[170:171]
	v_pk_fma_f32 v[52:53], v[52:53], v[154:155], v[168:169]
	v_pk_fma_f32 v[26:27], v[26:27], v[156:157], v[174:175]
	v_pk_fma_f32 v[24:25], v[24:25], v[158:159], v[172:173]
	s_nop 0
	s_waitcnt vmcnt(4)
	v_mov_b64_e32 v[132:133], v[192:193]
	v_mov_b64_e32 v[134:135], v[194:195]
	v_mov_b64_e32 v[164:165], v[196:197]
	v_mov_b64_e32 v[166:167], v[198:199]
	v_mov_b64_e32 v[168:169], v[200:201]
	v_mov_b64_e32 v[170:171], v[202:203]
	v_mov_b64_e32 v[172:173], v[204:205]
	v_mov_b64_e32 v[174:175], v[206:207]
	v_lshl_add_u64 v[224:225], v[224:225], 0, v[226:227]
	global_load_dwordx4 v[192:195], v[224:225], off
	global_load_dwordx4 v[196:199], v[224:225], off offset:64
	global_load_dwordx4 v[200:203], v[224:225], off offset:512
	global_load_dwordx4 v[204:207], v[224:225], off offset:576
	v_add_u32_e32 v176, 0xa0, v160
	v_ashrrev_i32_e32 v177, 31, v176
	v_lshlrev_b64 v[176:177], 12, v[176:177]
	v_lshl_add_u64 v[176:177], v[136:137], 0, v[176:177]
	v_lshl_add_u64 v[176:177], v[176:177], 0, v[140:141]
	s_waitcnt lgkmcnt(0)
	v_pk_mul_f32 v[134:135], v[134:135], s[0:1] op_sel_hi:[1,0]
	v_pk_mul_f32 v[132:133], v[132:133], s[0:1] op_sel_hi:[1,0]
	v_pk_mul_f32 v[166:167], v[166:167], s[0:1] op_sel_hi:[1,0]
	v_pk_mul_f32 v[164:165], v[164:165], s[0:1] op_sel_hi:[1,0]
	v_pk_mul_f32 v[170:171], v[170:171], s[0:1] op_sel_hi:[1,0]
	v_pk_mul_f32 v[168:169], v[168:169], s[0:1] op_sel_hi:[1,0]
	v_pk_mul_f32 v[174:175], v[174:175], s[0:1] op_sel_hi:[1,0]
	v_pk_mul_f32 v[172:173], v[172:173], s[0:1] op_sel_hi:[1,0]
	v_pk_fma_f32 v[122:123], v[122:123], v[142:143], v[134:135]
	v_pk_fma_f32 v[120:121], v[120:121], v[146:147], v[132:133]
	v_pk_fma_f32 v[98:99], v[98:99], v[148:149], v[166:167]
	v_pk_fma_f32 v[96:97], v[96:97], v[150:151], v[164:165]
	v_pk_fma_f32 v[62:63], v[62:63], v[152:153], v[170:171]
	v_pk_fma_f32 v[60:61], v[60:61], v[154:155], v[168:169]
	v_pk_fma_f32 v[34:35], v[34:35], v[156:157], v[174:175]
	v_pk_fma_f32 v[32:33], v[32:33], v[158:159], v[172:173]
	v_mbcnt_hi_u32_b32 v133, -1, v145
	s_nop 0
	s_waitcnt vmcnt(4)
	v_mov_b64_e32 v[164:165], v[208:209]
	v_mov_b64_e32 v[166:167], v[210:211]
	v_mov_b64_e32 v[168:169], v[212:213]
	v_mov_b64_e32 v[170:171], v[214:215]
	v_mov_b64_e32 v[172:173], v[216:217]
	v_mov_b64_e32 v[174:175], v[218:219]
	v_mov_b64_e32 v[176:177], v[220:221]
	v_mov_b64_e32 v[178:179], v[222:223]
	v_and_b32_e32 v134, 64, v133
	v_add_u32_e32 v139, 64, v134
	v_add_u32_e32 v134, 0xb0, v160
	v_ashrrev_i32_e32 v135, 31, v134
	v_lshlrev_b64 v[134:135], 12, v[134:135]
	v_lshl_add_u64 v[134:135], v[136:137], 0, v[134:135]
	v_lshl_add_u64 v[134:135], v[134:135], 0, v[140:141]
	v_mov_b32_e32 v160, v81
	v_pk_add_f32 v[160:161], v[160:161], v[180:181]
	v_pk_add_f32 v[180:181], v[182:183], v[184:185]
	v_add_f32_e32 v145, v160, v161
	v_pk_add_f32 v[160:161], v[180:181], v[180:181] op_sel_hi:[0,1]
	v_xor_b32_e32 v132, 16, v133
	v_add_f32_e32 v189, 0, v145
	v_mov_b32_e32 v160, v6
	v_cmp_lt_i32_e32 vcc, v132, v139
	v_pk_add_f32 v[160:161], v[160:161], v[188:189]
	v_xor_b32_e32 v145, 32, v133
	v_cndmask_b32_e32 v132, v133, v132, vcc
	v_lshlrev_b32_e32 v132, 2, v132
	v_cmp_lt_i32_e32 vcc, v145, v139
	s_waitcnt lgkmcnt(0)
;     __device__ __forceinline__ bool run(const f32x4 (&v)[2][2][4][2], const Unit& u, int wr, int wc, int fr, int fq, PG8_LAS unsigned char* lds, int wid, int lane) const {
;     ...
;                 float s = 0.f;
; #pragma unroll
;                 for (int bj = 0; bj < 2; ++bj)
; #pragma unroll
;                     for (int n = 0; n < 2; ++n) { const f32x4 x = v[ai][bj][m][n]; s += (x[0] + x[1]) + (x[2] + x[3]); }
;                 s += __shfl_xor(s, 16); s += __shfl_xor(s, 32);
;                 const float mw = s * (1.0f / 64.0f); float q = 0.f;
; #pragma unroll
;                 for (int bj = 0; bj < 2; ++bj)
; #pragma unroll
;                     for (int n = 0; n < 2; ++n) { const f32x4 d = v[ai][bj][m][n] - mw; q += (d[0] * d[0] + d[1] * d[1]) + (d[2] * d[2] + d[3] * d[3]); }
;                 q += __shfl_xor(q, 16); q += __shfl_xor(q, 32);
;                 if (fq == 0) P[(ai * HALF + wr * 64 + m * 16 + fr) * 4 + wc] = (f32x2v){mw, q};
;     __device__ __forceinline__ void fused(f32x4 (&acc)[2][2][4][2], const Unit& u, int wr, int wc, int fr, int fq, PG8_LAS unsigned char* lds, int wid, int lane) const {
;     ...
;         for (int ai = 0; ai < 2; ++ai)
; #pragma unroll
;             for (int m = 0; m < 4; ++m) { const size_t off = (size_t)(u.pm * BM + ai * HALF + wr * 64 + m * 16 + fr) * 1024 + col0;
; #pragma unroll
;                 for (int bj = 0; bj < 2; ++bj)
; #pragma unroll
;                     for (int n = 0; n < 2; ++n) { const f32x4 xv = *(const f32x4*)(xin + off + bj * HALF + n * 16); acc[ai][bj][m][n] = xv * ALPHA_ + acc[ai][bj][m][n]; }
;                 asm volatile("" : "+v"(acc[ai][0][m][0]), "+v"(acc[ai][0][m][1]), "+v"(acc[ai][1][m][0]), "+v"(acc[ai][1][m][1]));
;                 if (m & 1) asm volatile("" ::: "memory"); }
	v_pk_mul_f32 v[166:167], v[166:167], s[0:1] op_sel_hi:[1,0]
	v_pk_mul_f32 v[164:165], v[164:165], s[0:1] op_sel_hi:[1,0]
	v_pk_mul_f32 v[170:171], v[170:171], s[0:1] op_sel_hi:[1,0]
	v_pk_mul_f32 v[168:169], v[168:169], s[0:1] op_sel_hi:[1,0]
	v_pk_mul_f32 v[174:175], v[174:175], s[0:1] op_sel_hi:[1,0]
	v_pk_mul_f32 v[172:173], v[172:173], s[0:1] op_sel_hi:[1,0]
	v_pk_mul_f32 v[178:179], v[178:179], s[0:1] op_sel_hi:[1,0]
	v_pk_mul_f32 v[176:177], v[176:177], s[0:1] op_sel_hi:[1,0]
	v_pk_fma_f32 v[130:131], v[130:131], v[142:143], v[166:167]
	v_pk_fma_f32 v[128:129], v[128:129], v[146:147], v[164:165]
	v_pk_fma_f32 v[110:111], v[110:111], v[148:149], v[170:171]
	v_pk_fma_f32 v[108:109], v[108:109], v[150:151], v[168:169]
	v_pk_fma_f32 v[78:79], v[78:79], v[152:153], v[174:175]
	v_pk_fma_f32 v[76:77], v[76:77], v[154:155], v[172:173]
	v_pk_fma_f32 v[50:51], v[50:51], v[156:157], v[178:179]
	v_pk_fma_f32 v[48:49], v[48:49], v[158:159], v[176:177]
	v_cndmask_b32_e32 v133, v133, v145, vcc
	s_waitcnt vmcnt(0)
	v_mov_b64_e32 v[164:165], v[192:193]
	v_mov_b64_e32 v[166:167], v[194:195]
	v_mov_b64_e32 v[168:169], v[196:197]
	v_mov_b64_e32 v[170:171], v[198:199]
	v_mov_b64_e32 v[172:173], v[200:201]
	v_mov_b64_e32 v[174:175], v[202:203]
	v_mov_b64_e32 v[176:177], v[204:205]
	v_mov_b64_e32 v[178:179], v[206:207]
	v_add_f32_e32 v135, v20, v21
	v_mov_b32_e32 v134, v4
	v_pk_add_f32 v[134:135], v[134:135], v[186:187]
	v_lshlrev_b32_e32 v133, 2, v133
	v_pk_add_f32 v[134:135], v[134:135], v[160:161]
	s_waitcnt lgkmcnt(0)
	v_pk_mul_f32 v[164:165], v[164:165], s[0:1] op_sel_hi:[1,0]
	v_add_f32_e32 v134, v134, v135
	ds_bpermute_b32 v135, v132, v134
	v_pk_mul_f32 v[168:169], v[168:169], s[0:1] op_sel_hi:[1,0]
	v_pk_mul_f32 v[172:173], v[172:173], s[0:1] op_sel_hi:[1,0]
	v_pk_mul_f32 v[176:177], v[176:177], s[0:1] op_sel_hi:[1,0]
	v_pk_fma_f32 v[124:125], v[124:125], v[146:147], v[164:165]
	s_waitcnt lgkmcnt(0)
	v_add_f32_e32 v134, v134, v135
	ds_bpermute_b32 v135, v133, v134
	v_pk_fma_f32 v[116:117], v[116:117], v[150:151], v[168:169]
	v_pk_fma_f32 v[92:93], v[92:93], v[154:155], v[172:173]
	v_pk_fma_f32 v[64:65], v[64:65], v[158:159], v[176:177]
	s_waitcnt lgkmcnt(0)
	v_add_f32_e32 v135, v134, v135
	v_fmamk_f32 v139, v135, 0xbc800000, v83
	v_fmamk_f32 v160, v135, 0xbc800000, v81
	v_fmamk_f32 v180, v135, 0xbc800000, v47
	v_fmamk_f32 v182, v135, 0xbc800000, v45
	v_fmamk_f32 v134, v135, 0xbc800000, v82
	v_fmamk_f32 v145, v135, 0xbc800000, v80
	v_fmamk_f32 v161, v135, 0xbc800000, v46
	v_fmamk_f32 v181, v135, 0xbc800000, v44
	v_fmamk_f32 v184, v135, 0xbc800000, v23
	v_fmamk_f32 v186, v135, 0xbc800000, v21
	v_mul_f32_e32 v160, v160, v160
	v_mul_f32_e32 v139, v139, v139
	v_mul_f32_e32 v182, v182, v182
	v_mul_f32_e32 v180, v180, v180
	v_fmamk_f32 v183, v135, 0xbc800000, v22
	v_fmamk_f32 v185, v135, 0xbc800000, v20
	v_fmamk_f32 v188, v135, 0xbc800000, v7
	v_fmamk_f32 v190, v135, 0xbc800000, v5
	v_mul_f32_e32 v186, v186, v186
	v_mul_f32_e32 v184, v184, v184
	v_fmac_f32_e32 v160, v145, v145
	v_fmac_f32_e32 v139, v134, v134
	v_fmac_f32_e32 v182, v181, v181
	v_fmac_f32_e32 v180, v161, v161
	v_fmamk_f32 v187, v135, 0xbc800000, v6
	v_fmamk_f32 v189, v135, 0xbc800000, v4
	v_mul_f32_e32 v190, v190, v190
	v_mul_f32_e32 v188, v188, v188
	v_fmac_f32_e32 v186, v185, v185
	v_fmac_f32_e32 v184, v183, v183
	v_add_f32_e32 v134, v160, v139
	v_add_f32_e32 v139, v182, v180
	v_fmac_f32_e32 v190, v189, v189
	v_fmac_f32_e32 v188, v187, v187
	v_add_f32_e32 v145, v186, v184
	v_add_f32_e32 v134, v134, v139
	v_add_f32_e32 v160, v190, v188
	v_add_f32_e32 v134, v145, v134
	v_add_f32_e32 v139, v160, v134
	ds_bpermute_b32 v145, v132, v139
	v_pk_mul_f32 v[160:161], v[166:167], s[0:1] op_sel_hi:[1,0]
	v_pk_mul_f32 v[166:167], v[170:171], s[0:1] op_sel_hi:[1,0]
	v_pk_mul_f32 v[170:171], v[174:175], s[0:1] op_sel_hi:[1,0]
	v_pk_mul_f32 v[174:175], v[178:179], s[0:1] op_sel_hi:[1,0]
	s_waitcnt lgkmcnt(0)
	v_add_f32_e32 v139, v139, v145
	ds_bpermute_b32 v145, v133, v139
	v_pk_fma_f32 v[126:127], v[126:127], v[142:143], v[160:161]
	v_pk_fma_f32 v[118:119], v[118:119], v[148:149], v[166:167]
	v_pk_fma_f32 v[94:95], v[94:95], v[152:153], v[170:171]
	v_pk_fma_f32 v[66:67], v[66:67], v[156:157], v[174:175]
	v_and_b32_e32 v134, 63, v144
	s_lshl_b32 s0, s42, 3
	v_cmp_gt_u32_e32 vcc, 16, v134
	s_add_i32 s2, s0, 0
	s_and_saveexec_b64 s[0:1], vcc
	s_cbranch_execz .LBB0_1493
	s_lshl_b32 s4, s3, 11
	s_add_i32 s4, s2, s4
	v_mul_f32_e32 v142, 0x3c800000, v135
	v_lshl_add_u32 v135, v163, 5, s4
	s_waitcnt lgkmcnt(0)
	v_add_f32_e32 v143, v139, v145
	ds_write_b64 v135, v[142:143]
